# v192 plus scan-wave y of two steps per ds_write2_b64 (gen_scan6.py)
# speedup vs baseline: 1.0117x; 1.0011x over previous
.LBB0_390:
	s_and_b32 s3, s2, 1
	s_mul_i32 s8, s3, 0x5000
	v_add_u32_e32 v2, s8, v136
	s_mul_i32 s8, s2, 0xab
	s_bfe_u32 s8, s8, 0x70009
	s_mul_i32 s8, s8, 3
	s_sub_i32 s8, s2, s8
	s_and_b32 s8, s8, 0xff
	s_mulk_i32 s8, 0x1100
	v_add_u32_e32 v3, s8, v137
	v_lshl_add_u32 v1, s3, 12, v137
	v_add_u32_e32 v246, 0xd300, v1
	v_add_u32_e32 v247, 0xdb00, v1
	ds_read_b128 v[176:179], v2 offset:4096
	ds_read_b128 v[180:183], v2 offset:4112
	ds_read_b128 v[200:203], v2 offset:12288
	ds_read_b128 v[204:207], v2 offset:12304
	ds_read_b64 v[216:217], v3 offset:40960
	ds_read_b128 v[184:187], v2 offset:0
	ds_read_b128 v[188:191], v2 offset:16
	ds_read_b128 v[192:195], v2 offset:8192
	ds_read_b128 v[196:199], v2 offset:8208
	s_waitcnt lgkmcnt(8)
	v_pk_mul_f32 v[164:165], v[72:73], v[176:177]
	v_pk_mul_f32 v[166:167], v[80:81], v[176:177]
	ds_read_b128 v[208:211], v2 offset:16384
	v_pk_fma_f32 v[164:165], v[74:75], v[178:179], v[164:165]
	v_pk_fma_f32 v[166:167], v[82:83], v[178:179], v[166:167]
	ds_read_b128 v[212:215], v2 offset:16400
	s_waitcnt lgkmcnt(9)
	v_pk_fma_f32 v[164:165], v[76:77], v[180:181], v[164:165]
	v_pk_fma_f32 v[166:167], v[84:85], v[180:181], v[166:167]
	ds_read_b128 v[4:7], v2 offset:4352
	v_pk_fma_f32 v[164:165], v[78:79], v[182:183], v[164:165]
	v_pk_fma_f32 v[166:167], v[86:87], v[182:183], v[166:167]
	ds_read_b128 v[8:11], v2 offset:4368
	s_waitcnt lgkmcnt(8)
	v_pk_mul_f32 v[218:219], v[216:217], v[200:201] op_sel_hi:[0,1]
	v_pk_mul_f32 v[226:227], v[216:217], v[200:201] op_sel:[1,0]
	ds_read_b128 v[40:43], v2 offset:12544
	v_pk_mul_f32 v[220:221], v[216:217], v[202:203] op_sel_hi:[0,1]
	v_pk_mul_f32 v[228:229], v[216:217], v[202:203] op_sel:[1,0]
	ds_read_b128 v[44:47], v2 offset:12560
	v_pk_mul_f32 v[222:223], v[216:217], v[204:205] op_sel_hi:[0,1]
	v_pk_mul_f32 v[230:231], v[216:217], v[204:205] op_sel:[1,0]
	ds_read_b64 v[26:27], v3 offset:41216
	v_pk_mul_f32 v[224:225], v[216:217], v[206:207] op_sel_hi:[0,1]
	v_pk_mul_f32 v[234:235], v[216:217], v[206:207] op_sel:[1,0]
	ds_read_b128 v[12:15], v2 offset:256
	v_add_f32_e32 v172, v164, v165
	v_add_f32_e32 v174, v166, v167
	ds_read_b128 v[28:31], v2 offset:272
	s_waitcnt lgkmcnt(12)
	v_pk_fma_f32 v[218:219], v[72:73], v[184:185], v[218:219]
	v_pk_fma_f32 v[226:227], v[80:81], v[184:185], v[226:227]
	ds_read_b128 v[32:35], v2 offset:8448
	v_pk_fma_f32 v[220:221], v[74:75], v[186:187], v[220:221]
	v_pk_fma_f32 v[228:229], v[82:83], v[186:187], v[228:229]
	ds_read_b128 v[36:39], v2 offset:8464
	v_add_f32_dpp v172, v172, v172 quad_perm:[1,0,3,2] row_mask:0xf bank_mask:0xf bound_ctrl:1
	v_add_f32_dpp v174, v174, v174 quad_perm:[1,0,3,2] row_mask:0xf bank_mask:0xf bound_ctrl:1
	s_waitcnt lgkmcnt(13)
	v_pk_fma_f32 v[222:223], v[76:77], v[188:189], v[222:223]
	v_pk_fma_f32 v[230:231], v[84:85], v[188:189], v[230:231]
	v_pk_fma_f32 v[224:225], v[78:79], v[190:191], v[224:225]
	v_pk_fma_f32 v[234:235], v[86:87], v[190:191], v[234:235]
	v_add_f32_dpp v172, v172, v172 quad_perm:[2,3,0,1] row_mask:0xf bank_mask:0xf bound_ctrl:1
	v_add_f32_dpp v174, v174, v174 quad_perm:[2,3,0,1] row_mask:0xf bank_mask:0xf bound_ctrl:1
	s_nop 0
	v_add_f32_dpp v172, v172, v172 row_half_mirror row_mask:0xf bank_mask:0xf bound_ctrl:1
	v_add_f32_dpp v174, v174, v174 row_half_mirror row_mask:0xf bank_mask:0xf bound_ctrl:1
	s_waitcnt lgkmcnt(12)
	v_pk_fma_f32 v[72:73], v[192:193], v[172:173], v[218:219] op_sel_hi:[1,0,1]
	v_pk_fma_f32 v[80:81], v[192:193], v[174:175], v[226:227] op_sel_hi:[1,0,1]
	v_pk_fma_f32 v[74:75], v[194:195], v[172:173], v[220:221] op_sel_hi:[1,0,1]
	v_pk_fma_f32 v[82:83], v[194:195], v[174:175], v[228:229] op_sel_hi:[1,0,1]
	s_waitcnt lgkmcnt(11)
	v_pk_fma_f32 v[76:77], v[196:197], v[172:173], v[222:223] op_sel_hi:[1,0,1]
	v_pk_fma_f32 v[84:85], v[196:197], v[174:175], v[230:231] op_sel_hi:[1,0,1]
	v_pk_fma_f32 v[78:79], v[198:199], v[172:173], v[224:225] op_sel_hi:[1,0,1]
	v_pk_fma_f32 v[86:87], v[198:199], v[174:175], v[234:235] op_sel_hi:[1,0,1]
	s_waitcnt lgkmcnt(8)
	v_pk_mul_f32 v[164:165], v[72:73], v[4:5]
	v_pk_mul_f32 v[166:167], v[80:81], v[4:5]
	ds_read_b128 v[48:51], v2 offset:16640
	v_pk_mul_f32 v[168:169], v[72:73], v[208:209]
	v_pk_mul_f32 v[170:171], v[80:81], v[208:209]
	ds_read_b128 v[52:55], v2 offset:16656
	v_pk_fma_f32 v[164:165], v[74:75], v[6:7], v[164:165]
	v_pk_fma_f32 v[166:167], v[82:83], v[6:7], v[166:167]
	ds_read_b128 v[176:179], v2 offset:4608
	v_pk_fma_f32 v[168:169], v[74:75], v[210:211], v[168:169]
	v_pk_fma_f32 v[170:171], v[82:83], v[210:211], v[170:171]
	ds_read_b128 v[180:183], v2 offset:4624
	s_waitcnt lgkmcnt(11)
	v_pk_fma_f32 v[164:165], v[76:77], v[8:9], v[164:165]
	v_pk_fma_f32 v[166:167], v[84:85], v[8:9], v[166:167]
	ds_read_b128 v[200:203], v2 offset:12800
	v_pk_fma_f32 v[168:169], v[76:77], v[212:213], v[168:169]
	v_pk_fma_f32 v[170:171], v[84:85], v[212:213], v[170:171]
	ds_read_b128 v[204:207], v2 offset:12816
	v_pk_fma_f32 v[164:165], v[78:79], v[10:11], v[164:165]
	v_pk_fma_f32 v[166:167], v[86:87], v[10:11], v[166:167]
	ds_read_b64 v[216:217], v3 offset:41472
	v_pk_fma_f32 v[168:169], v[78:79], v[214:215], v[168:169]
	v_pk_fma_f32 v[170:171], v[86:87], v[214:215], v[170:171]
	ds_read_b128 v[184:187], v2 offset:512
	s_waitcnt lgkmcnt(12)
	v_pk_mul_f32 v[218:219], v[26:27], v[40:41] op_sel_hi:[0,1]
	v_pk_mul_f32 v[226:227], v[26:27], v[40:41] op_sel:[1,0]
	ds_read_b128 v[188:191], v2 offset:528
	v_pk_mul_f32 v[220:221], v[26:27], v[42:43] op_sel_hi:[0,1]
	v_pk_mul_f32 v[228:229], v[26:27], v[42:43] op_sel:[1,0]
	ds_read_b128 v[192:195], v2 offset:8704
	v_pk_mul_f32 v[222:223], v[26:27], v[44:45] op_sel_hi:[0,1]
	v_pk_mul_f32 v[230:231], v[26:27], v[44:45] op_sel:[1,0]
	ds_read_b128 v[196:199], v2 offset:8720
	v_pk_mul_f32 v[224:225], v[26:27], v[46:47] op_sel_hi:[0,1]
	v_pk_mul_f32 v[234:235], v[26:27], v[46:47] op_sel:[1,0]
	v_add_f32_e32 v172, v164, v165
	v_add_f32_e32 v174, v166, v167
	v_add_f32_e32 v160, v168, v169
	v_add_f32_e32 v161, v170, v171
	s_waitcnt lgkmcnt(14)
	v_pk_fma_f32 v[218:219], v[72:73], v[12:13], v[218:219]
	v_pk_fma_f32 v[226:227], v[80:81], v[12:13], v[226:227]
	v_pk_fma_f32 v[220:221], v[74:75], v[14:15], v[220:221]
	v_pk_fma_f32 v[228:229], v[82:83], v[14:15], v[228:229]
	v_add_f32_dpp v172, v172, v172 quad_perm:[1,0,3,2] row_mask:0xf bank_mask:0xf bound_ctrl:1
	v_add_f32_dpp v174, v174, v174 quad_perm:[1,0,3,2] row_mask:0xf bank_mask:0xf bound_ctrl:1
	v_add_f32_dpp v160, v160, v160 quad_perm:[1,0,3,2] row_mask:0xf bank_mask:0xf bound_ctrl:1
	v_add_f32_dpp v161, v161, v161 quad_perm:[1,0,3,2] row_mask:0xf bank_mask:0xf bound_ctrl:1
	s_waitcnt lgkmcnt(13)
	v_pk_fma_f32 v[222:223], v[76:77], v[28:29], v[222:223]
	v_pk_fma_f32 v[230:231], v[84:85], v[28:29], v[230:231]
	v_pk_fma_f32 v[224:225], v[78:79], v[30:31], v[224:225]
	v_pk_fma_f32 v[234:235], v[86:87], v[30:31], v[234:235]
	v_add_f32_dpp v172, v172, v172 quad_perm:[2,3,0,1] row_mask:0xf bank_mask:0xf bound_ctrl:1
	v_add_f32_dpp v174, v174, v174 quad_perm:[2,3,0,1] row_mask:0xf bank_mask:0xf bound_ctrl:1
	v_add_f32_dpp v160, v160, v160 quad_perm:[2,3,0,1] row_mask:0xf bank_mask:0xf bound_ctrl:1
	v_add_f32_dpp v161, v161, v161 quad_perm:[2,3,0,1] row_mask:0xf bank_mask:0xf bound_ctrl:1
	v_add_f32_dpp v172, v172, v172 row_half_mirror row_mask:0xf bank_mask:0xf bound_ctrl:1
	v_add_f32_dpp v174, v174, v174 row_half_mirror row_mask:0xf bank_mask:0xf bound_ctrl:1
	v_add_f32_dpp v160, v160, v160 row_half_mirror row_mask:0xf bank_mask:0xf bound_ctrl:1
	v_add_f32_dpp v161, v161, v161 row_half_mirror row_mask:0xf bank_mask:0xf bound_ctrl:1
	s_waitcnt lgkmcnt(12)
	v_pk_fma_f32 v[72:73], v[32:33], v[172:173], v[218:219] op_sel_hi:[1,0,1]
	v_pk_fma_f32 v[80:81], v[32:33], v[174:175], v[226:227] op_sel_hi:[1,0,1]
	v_pk_fma_f32 v[74:75], v[34:35], v[172:173], v[220:221] op_sel_hi:[1,0,1]
	v_pk_fma_f32 v[82:83], v[34:35], v[174:175], v[228:229] op_sel_hi:[1,0,1]
	s_waitcnt lgkmcnt(11)
	v_pk_fma_f32 v[76:77], v[36:37], v[172:173], v[222:223] op_sel_hi:[1,0,1]
	v_pk_fma_f32 v[84:85], v[36:37], v[174:175], v[230:231] op_sel_hi:[1,0,1]
	v_pk_fma_f32 v[78:79], v[38:39], v[172:173], v[224:225] op_sel_hi:[1,0,1]
	v_pk_fma_f32 v[86:87], v[38:39], v[174:175], v[234:235] op_sel_hi:[1,0,1]
	s_waitcnt lgkmcnt(8)
	v_pk_mul_f32 v[164:165], v[72:73], v[176:177]
	v_pk_mul_f32 v[166:167], v[80:81], v[176:177]
	ds_read_b128 v[208:211], v2 offset:16896
	v_pk_mul_f32 v[168:169], v[72:73], v[48:49]
	v_pk_mul_f32 v[170:171], v[80:81], v[48:49]
	ds_read_b128 v[212:215], v2 offset:16912
	v_pk_fma_f32 v[164:165], v[74:75], v[178:179], v[164:165]
	v_pk_fma_f32 v[166:167], v[82:83], v[178:179], v[166:167]
	ds_read_b128 v[4:7], v2 offset:4864
	v_pk_fma_f32 v[168:169], v[74:75], v[50:51], v[168:169]
	v_pk_fma_f32 v[170:171], v[82:83], v[50:51], v[170:171]
	ds_read_b128 v[8:11], v2 offset:4880
	s_waitcnt lgkmcnt(11)
	v_pk_fma_f32 v[164:165], v[76:77], v[180:181], v[164:165]
	v_pk_fma_f32 v[166:167], v[84:85], v[180:181], v[166:167]
	ds_read_b128 v[40:43], v2 offset:13056
	v_pk_fma_f32 v[168:169], v[76:77], v[52:53], v[168:169]
	v_pk_fma_f32 v[170:171], v[84:85], v[52:53], v[170:171]
	ds_read_b128 v[44:47], v2 offset:13072
	v_pk_fma_f32 v[164:165], v[78:79], v[182:183], v[164:165]
	v_pk_fma_f32 v[166:167], v[86:87], v[182:183], v[166:167]
	ds_read_b64 v[26:27], v3 offset:41728
	v_pk_fma_f32 v[168:169], v[78:79], v[54:55], v[168:169]
	v_pk_fma_f32 v[170:171], v[86:87], v[54:55], v[170:171]
	ds_read_b128 v[12:15], v2 offset:768
	s_waitcnt lgkmcnt(12)
	v_pk_mul_f32 v[218:219], v[216:217], v[200:201] op_sel_hi:[0,1]
	v_pk_mul_f32 v[226:227], v[216:217], v[200:201] op_sel:[1,0]
	ds_read_b128 v[28:31], v2 offset:784
	v_pk_mul_f32 v[220:221], v[216:217], v[202:203] op_sel_hi:[0,1]
	v_pk_mul_f32 v[228:229], v[216:217], v[202:203] op_sel:[1,0]
	ds_read_b128 v[32:35], v2 offset:8960
	v_pk_mul_f32 v[222:223], v[216:217], v[204:205] op_sel_hi:[0,1]
	v_pk_mul_f32 v[230:231], v[216:217], v[204:205] op_sel:[1,0]
	ds_read_b128 v[36:39], v2 offset:8976
	v_pk_mul_f32 v[224:225], v[216:217], v[206:207] op_sel_hi:[0,1]
	v_pk_mul_f32 v[234:235], v[216:217], v[206:207] op_sel:[1,0]
	v_add_f32_e32 v172, v164, v165
	v_add_f32_e32 v174, v166, v167
	v_add_f32_e32 v244, v168, v169
	v_add_f32_e32 v245, v170, v171
	s_waitcnt lgkmcnt(14)
	v_pk_fma_f32 v[218:219], v[72:73], v[184:185], v[218:219]
	v_pk_fma_f32 v[226:227], v[80:81], v[184:185], v[226:227]
	v_pk_fma_f32 v[220:221], v[74:75], v[186:187], v[220:221]
	v_pk_fma_f32 v[228:229], v[82:83], v[186:187], v[228:229]
	v_add_f32_dpp v172, v172, v172 quad_perm:[1,0,3,2] row_mask:0xf bank_mask:0xf bound_ctrl:1
	v_add_f32_dpp v174, v174, v174 quad_perm:[1,0,3,2] row_mask:0xf bank_mask:0xf bound_ctrl:1
	v_add_f32_dpp v244, v244, v244 quad_perm:[1,0,3,2] row_mask:0xf bank_mask:0xf bound_ctrl:1
	v_add_f32_dpp v245, v245, v245 quad_perm:[1,0,3,2] row_mask:0xf bank_mask:0xf bound_ctrl:1
	s_waitcnt lgkmcnt(13)
	v_pk_fma_f32 v[222:223], v[76:77], v[188:189], v[222:223]
	v_pk_fma_f32 v[230:231], v[84:85], v[188:189], v[230:231]
	v_pk_fma_f32 v[224:225], v[78:79], v[190:191], v[224:225]
	v_pk_fma_f32 v[234:235], v[86:87], v[190:191], v[234:235]
	v_add_f32_dpp v172, v172, v172 quad_perm:[2,3,0,1] row_mask:0xf bank_mask:0xf bound_ctrl:1
	v_add_f32_dpp v174, v174, v174 quad_perm:[2,3,0,1] row_mask:0xf bank_mask:0xf bound_ctrl:1
	v_add_f32_dpp v244, v244, v244 quad_perm:[2,3,0,1] row_mask:0xf bank_mask:0xf bound_ctrl:1
	v_add_f32_dpp v245, v245, v245 quad_perm:[2,3,0,1] row_mask:0xf bank_mask:0xf bound_ctrl:1
	v_add_f32_dpp v172, v172, v172 row_half_mirror row_mask:0xf bank_mask:0xf bound_ctrl:1
	v_add_f32_dpp v174, v174, v174 row_half_mirror row_mask:0xf bank_mask:0xf bound_ctrl:1
	v_add_f32_dpp v244, v244, v244 row_half_mirror row_mask:0xf bank_mask:0xf bound_ctrl:1
	v_add_f32_dpp v245, v245, v245 row_half_mirror row_mask:0xf bank_mask:0xf bound_ctrl:1
	s_waitcnt lgkmcnt(12)
	v_pk_fma_f32 v[72:73], v[192:193], v[172:173], v[218:219] op_sel_hi:[1,0,1]
	v_pk_fma_f32 v[80:81], v[192:193], v[174:175], v[226:227] op_sel_hi:[1,0,1]
	v_pk_fma_f32 v[74:75], v[194:195], v[172:173], v[220:221] op_sel_hi:[1,0,1]
	v_pk_fma_f32 v[82:83], v[194:195], v[174:175], v[228:229] op_sel_hi:[1,0,1]
	s_waitcnt lgkmcnt(11)
	v_pk_fma_f32 v[76:77], v[196:197], v[172:173], v[222:223] op_sel_hi:[1,0,1]
	v_pk_fma_f32 v[84:85], v[196:197], v[174:175], v[230:231] op_sel_hi:[1,0,1]
	v_pk_fma_f32 v[78:79], v[198:199], v[172:173], v[224:225] op_sel_hi:[1,0,1]
	v_pk_fma_f32 v[86:87], v[198:199], v[174:175], v[234:235] op_sel_hi:[1,0,1]
	ds_write2_b64 v246, v[160:161], v[244:245] offset1:32
	s_waitcnt lgkmcnt(9)
	v_pk_mul_f32 v[164:165], v[72:73], v[4:5]
	v_pk_mul_f32 v[166:167], v[80:81], v[4:5]
	ds_read_b128 v[48:51], v2 offset:17152
	v_pk_mul_f32 v[168:169], v[72:73], v[208:209]
	v_pk_mul_f32 v[170:171], v[80:81], v[208:209]
	ds_read_b128 v[52:55], v2 offset:17168
	v_pk_fma_f32 v[164:165], v[74:75], v[6:7], v[164:165]
	v_pk_fma_f32 v[166:167], v[82:83], v[6:7], v[166:167]
	ds_read_b128 v[176:179], v2 offset:5120
	v_pk_fma_f32 v[168:169], v[74:75], v[210:211], v[168:169]
	v_pk_fma_f32 v[170:171], v[82:83], v[210:211], v[170:171]
	ds_read_b128 v[180:183], v2 offset:5136
	s_waitcnt lgkmcnt(12)
	v_pk_fma_f32 v[164:165], v[76:77], v[8:9], v[164:165]
	v_pk_fma_f32 v[166:167], v[84:85], v[8:9], v[166:167]
	ds_read_b128 v[200:203], v2 offset:13312
	v_pk_fma_f32 v[168:169], v[76:77], v[212:213], v[168:169]
	v_pk_fma_f32 v[170:171], v[84:85], v[212:213], v[170:171]
	ds_read_b128 v[204:207], v2 offset:13328
	v_pk_fma_f32 v[164:165], v[78:79], v[10:11], v[164:165]
	v_pk_fma_f32 v[166:167], v[86:87], v[10:11], v[166:167]
	ds_read_b64 v[216:217], v3 offset:41984
	v_pk_fma_f32 v[168:169], v[78:79], v[214:215], v[168:169]
	v_pk_fma_f32 v[170:171], v[86:87], v[214:215], v[170:171]
	ds_read_b128 v[184:187], v2 offset:1024
	s_waitcnt lgkmcnt(13)
	v_pk_mul_f32 v[218:219], v[26:27], v[40:41] op_sel_hi:[0,1]
	v_pk_mul_f32 v[226:227], v[26:27], v[40:41] op_sel:[1,0]
	ds_read_b128 v[188:191], v2 offset:1040
	v_pk_mul_f32 v[220:221], v[26:27], v[42:43] op_sel_hi:[0,1]
	v_pk_mul_f32 v[228:229], v[26:27], v[42:43] op_sel:[1,0]
	ds_read_b128 v[192:195], v2 offset:9216
	v_pk_mul_f32 v[222:223], v[26:27], v[44:45] op_sel_hi:[0,1]
	v_pk_mul_f32 v[230:231], v[26:27], v[44:45] op_sel:[1,0]
	ds_read_b128 v[196:199], v2 offset:9232
	v_pk_mul_f32 v[224:225], v[26:27], v[46:47] op_sel_hi:[0,1]
	v_pk_mul_f32 v[234:235], v[26:27], v[46:47] op_sel:[1,0]
	v_add_f32_e32 v172, v164, v165
	v_add_f32_e32 v174, v166, v167
	v_add_f32_e32 v160, v168, v169
	v_add_f32_e32 v161, v170, v171
	s_waitcnt lgkmcnt(15)
	v_pk_fma_f32 v[218:219], v[72:73], v[12:13], v[218:219]
	v_pk_fma_f32 v[226:227], v[80:81], v[12:13], v[226:227]
	v_pk_fma_f32 v[220:221], v[74:75], v[14:15], v[220:221]
	v_pk_fma_f32 v[228:229], v[82:83], v[14:15], v[228:229]
	v_add_f32_dpp v172, v172, v172 quad_perm:[1,0,3,2] row_mask:0xf bank_mask:0xf bound_ctrl:1
	v_add_f32_dpp v174, v174, v174 quad_perm:[1,0,3,2] row_mask:0xf bank_mask:0xf bound_ctrl:1
	v_add_f32_dpp v160, v160, v160 quad_perm:[1,0,3,2] row_mask:0xf bank_mask:0xf bound_ctrl:1
	v_add_f32_dpp v161, v161, v161 quad_perm:[1,0,3,2] row_mask:0xf bank_mask:0xf bound_ctrl:1
	s_waitcnt lgkmcnt(14)
	v_pk_fma_f32 v[222:223], v[76:77], v[28:29], v[222:223]
	v_pk_fma_f32 v[230:231], v[84:85], v[28:29], v[230:231]
	v_pk_fma_f32 v[224:225], v[78:79], v[30:31], v[224:225]
	v_pk_fma_f32 v[234:235], v[86:87], v[30:31], v[234:235]
	v_add_f32_dpp v172, v172, v172 quad_perm:[2,3,0,1] row_mask:0xf bank_mask:0xf bound_ctrl:1
	v_add_f32_dpp v174, v174, v174 quad_perm:[2,3,0,1] row_mask:0xf bank_mask:0xf bound_ctrl:1
	v_add_f32_dpp v160, v160, v160 quad_perm:[2,3,0,1] row_mask:0xf bank_mask:0xf bound_ctrl:1
	v_add_f32_dpp v161, v161, v161 quad_perm:[2,3,0,1] row_mask:0xf bank_mask:0xf bound_ctrl:1
	v_add_f32_dpp v172, v172, v172 row_half_mirror row_mask:0xf bank_mask:0xf bound_ctrl:1
	v_add_f32_dpp v174, v174, v174 row_half_mirror row_mask:0xf bank_mask:0xf bound_ctrl:1
	v_add_f32_dpp v160, v160, v160 row_half_mirror row_mask:0xf bank_mask:0xf bound_ctrl:1
	v_add_f32_dpp v161, v161, v161 row_half_mirror row_mask:0xf bank_mask:0xf bound_ctrl:1
	s_waitcnt lgkmcnt(13)
	v_pk_fma_f32 v[72:73], v[32:33], v[172:173], v[218:219] op_sel_hi:[1,0,1]
	v_pk_fma_f32 v[80:81], v[32:33], v[174:175], v[226:227] op_sel_hi:[1,0,1]
	v_pk_fma_f32 v[74:75], v[34:35], v[172:173], v[220:221] op_sel_hi:[1,0,1]
	v_pk_fma_f32 v[82:83], v[34:35], v[174:175], v[228:229] op_sel_hi:[1,0,1]
	s_waitcnt lgkmcnt(12)
	v_pk_fma_f32 v[76:77], v[36:37], v[172:173], v[222:223] op_sel_hi:[1,0,1]
	v_pk_fma_f32 v[84:85], v[36:37], v[174:175], v[230:231] op_sel_hi:[1,0,1]
	v_pk_fma_f32 v[78:79], v[38:39], v[172:173], v[224:225] op_sel_hi:[1,0,1]
	v_pk_fma_f32 v[86:87], v[38:39], v[174:175], v[234:235] op_sel_hi:[1,0,1]
	s_waitcnt lgkmcnt(8)
	v_pk_mul_f32 v[164:165], v[72:73], v[176:177]
	v_pk_mul_f32 v[166:167], v[80:81], v[176:177]
	ds_read_b128 v[208:211], v2 offset:17408
	v_pk_mul_f32 v[168:169], v[72:73], v[48:49]
	v_pk_mul_f32 v[170:171], v[80:81], v[48:49]
	ds_read_b128 v[212:215], v2 offset:17424
	v_pk_fma_f32 v[164:165], v[74:75], v[178:179], v[164:165]
	v_pk_fma_f32 v[166:167], v[82:83], v[178:179], v[166:167]
	ds_read_b128 v[4:7], v2 offset:5376
	v_pk_fma_f32 v[168:169], v[74:75], v[50:51], v[168:169]
	v_pk_fma_f32 v[170:171], v[82:83], v[50:51], v[170:171]
	ds_read_b128 v[8:11], v2 offset:5392
	s_waitcnt lgkmcnt(11)
	v_pk_fma_f32 v[164:165], v[76:77], v[180:181], v[164:165]
	v_pk_fma_f32 v[166:167], v[84:85], v[180:181], v[166:167]
	ds_read_b128 v[40:43], v2 offset:13568
	v_pk_fma_f32 v[168:169], v[76:77], v[52:53], v[168:169]
	v_pk_fma_f32 v[170:171], v[84:85], v[52:53], v[170:171]
	ds_read_b128 v[44:47], v2 offset:13584
	v_pk_fma_f32 v[164:165], v[78:79], v[182:183], v[164:165]
	v_pk_fma_f32 v[166:167], v[86:87], v[182:183], v[166:167]
	ds_read_b64 v[26:27], v3 offset:42240
	v_pk_fma_f32 v[168:169], v[78:79], v[54:55], v[168:169]
	v_pk_fma_f32 v[170:171], v[86:87], v[54:55], v[170:171]
	ds_read_b128 v[12:15], v2 offset:1280
	s_waitcnt lgkmcnt(12)
	v_pk_mul_f32 v[218:219], v[216:217], v[200:201] op_sel_hi:[0,1]
	v_pk_mul_f32 v[226:227], v[216:217], v[200:201] op_sel:[1,0]
	ds_read_b128 v[28:31], v2 offset:1296
	v_pk_mul_f32 v[220:221], v[216:217], v[202:203] op_sel_hi:[0,1]
	v_pk_mul_f32 v[228:229], v[216:217], v[202:203] op_sel:[1,0]
	ds_read_b128 v[32:35], v2 offset:9472
	v_pk_mul_f32 v[222:223], v[216:217], v[204:205] op_sel_hi:[0,1]
	v_pk_mul_f32 v[230:231], v[216:217], v[204:205] op_sel:[1,0]
	ds_read_b128 v[36:39], v2 offset:9488
	v_pk_mul_f32 v[224:225], v[216:217], v[206:207] op_sel_hi:[0,1]
	v_pk_mul_f32 v[234:235], v[216:217], v[206:207] op_sel:[1,0]
	v_add_f32_e32 v172, v164, v165
	v_add_f32_e32 v174, v166, v167
	v_add_f32_e32 v244, v168, v169
	v_add_f32_e32 v245, v170, v171
	s_waitcnt lgkmcnt(14)
	v_pk_fma_f32 v[218:219], v[72:73], v[184:185], v[218:219]
	v_pk_fma_f32 v[226:227], v[80:81], v[184:185], v[226:227]
	v_pk_fma_f32 v[220:221], v[74:75], v[186:187], v[220:221]
	v_pk_fma_f32 v[228:229], v[82:83], v[186:187], v[228:229]
	v_add_f32_dpp v172, v172, v172 quad_perm:[1,0,3,2] row_mask:0xf bank_mask:0xf bound_ctrl:1
	v_add_f32_dpp v174, v174, v174 quad_perm:[1,0,3,2] row_mask:0xf bank_mask:0xf bound_ctrl:1
	v_add_f32_dpp v244, v244, v244 quad_perm:[1,0,3,2] row_mask:0xf bank_mask:0xf bound_ctrl:1
	v_add_f32_dpp v245, v245, v245 quad_perm:[1,0,3,2] row_mask:0xf bank_mask:0xf bound_ctrl:1
	s_waitcnt lgkmcnt(13)
	v_pk_fma_f32 v[222:223], v[76:77], v[188:189], v[222:223]
	v_pk_fma_f32 v[230:231], v[84:85], v[188:189], v[230:231]
	v_pk_fma_f32 v[224:225], v[78:79], v[190:191], v[224:225]
	v_pk_fma_f32 v[234:235], v[86:87], v[190:191], v[234:235]
	v_add_f32_dpp v172, v172, v172 quad_perm:[2,3,0,1] row_mask:0xf bank_mask:0xf bound_ctrl:1
	v_add_f32_dpp v174, v174, v174 quad_perm:[2,3,0,1] row_mask:0xf bank_mask:0xf bound_ctrl:1
	v_add_f32_dpp v244, v244, v244 quad_perm:[2,3,0,1] row_mask:0xf bank_mask:0xf bound_ctrl:1
	v_add_f32_dpp v245, v245, v245 quad_perm:[2,3,0,1] row_mask:0xf bank_mask:0xf bound_ctrl:1
	v_add_f32_dpp v172, v172, v172 row_half_mirror row_mask:0xf bank_mask:0xf bound_ctrl:1
	v_add_f32_dpp v174, v174, v174 row_half_mirror row_mask:0xf bank_mask:0xf bound_ctrl:1
	v_add_f32_dpp v244, v244, v244 row_half_mirror row_mask:0xf bank_mask:0xf bound_ctrl:1
	v_add_f32_dpp v245, v245, v245 row_half_mirror row_mask:0xf bank_mask:0xf bound_ctrl:1
	s_waitcnt lgkmcnt(12)
	v_pk_fma_f32 v[72:73], v[192:193], v[172:173], v[218:219] op_sel_hi:[1,0,1]
	v_pk_fma_f32 v[80:81], v[192:193], v[174:175], v[226:227] op_sel_hi:[1,0,1]
	v_pk_fma_f32 v[74:75], v[194:195], v[172:173], v[220:221] op_sel_hi:[1,0,1]
	v_pk_fma_f32 v[82:83], v[194:195], v[174:175], v[228:229] op_sel_hi:[1,0,1]
	s_waitcnt lgkmcnt(11)
	v_pk_fma_f32 v[76:77], v[196:197], v[172:173], v[222:223] op_sel_hi:[1,0,1]
	v_pk_fma_f32 v[84:85], v[196:197], v[174:175], v[230:231] op_sel_hi:[1,0,1]
	v_pk_fma_f32 v[78:79], v[198:199], v[172:173], v[224:225] op_sel_hi:[1,0,1]
	v_pk_fma_f32 v[86:87], v[198:199], v[174:175], v[234:235] op_sel_hi:[1,0,1]
	ds_write2_b64 v246, v[160:161], v[244:245] offset0:64 offset1:96
	s_waitcnt lgkmcnt(9)
	v_pk_mul_f32 v[164:165], v[72:73], v[4:5]
	v_pk_mul_f32 v[166:167], v[80:81], v[4:5]
	ds_read_b128 v[48:51], v2 offset:17664
	v_pk_mul_f32 v[168:169], v[72:73], v[208:209]
	v_pk_mul_f32 v[170:171], v[80:81], v[208:209]
	ds_read_b128 v[52:55], v2 offset:17680
	v_pk_fma_f32 v[164:165], v[74:75], v[6:7], v[164:165]
	v_pk_fma_f32 v[166:167], v[82:83], v[6:7], v[166:167]
	ds_read_b128 v[176:179], v2 offset:5632
	v_pk_fma_f32 v[168:169], v[74:75], v[210:211], v[168:169]
	v_pk_fma_f32 v[170:171], v[82:83], v[210:211], v[170:171]
	ds_read_b128 v[180:183], v2 offset:5648
	s_waitcnt lgkmcnt(12)
	v_pk_fma_f32 v[164:165], v[76:77], v[8:9], v[164:165]
	v_pk_fma_f32 v[166:167], v[84:85], v[8:9], v[166:167]
	ds_read_b128 v[200:203], v2 offset:13824
	v_pk_fma_f32 v[168:169], v[76:77], v[212:213], v[168:169]
	v_pk_fma_f32 v[170:171], v[84:85], v[212:213], v[170:171]
	ds_read_b128 v[204:207], v2 offset:13840
	v_pk_fma_f32 v[164:165], v[78:79], v[10:11], v[164:165]
	v_pk_fma_f32 v[166:167], v[86:87], v[10:11], v[166:167]
	ds_read_b64 v[216:217], v3 offset:42496
	v_pk_fma_f32 v[168:169], v[78:79], v[214:215], v[168:169]
	v_pk_fma_f32 v[170:171], v[86:87], v[214:215], v[170:171]
	ds_read_b128 v[184:187], v2 offset:1536
	s_waitcnt lgkmcnt(13)
	v_pk_mul_f32 v[218:219], v[26:27], v[40:41] op_sel_hi:[0,1]
	v_pk_mul_f32 v[226:227], v[26:27], v[40:41] op_sel:[1,0]
	ds_read_b128 v[188:191], v2 offset:1552
	v_pk_mul_f32 v[220:221], v[26:27], v[42:43] op_sel_hi:[0,1]
	v_pk_mul_f32 v[228:229], v[26:27], v[42:43] op_sel:[1,0]
	ds_read_b128 v[192:195], v2 offset:9728
	v_pk_mul_f32 v[222:223], v[26:27], v[44:45] op_sel_hi:[0,1]
	v_pk_mul_f32 v[230:231], v[26:27], v[44:45] op_sel:[1,0]
	ds_read_b128 v[196:199], v2 offset:9744
	v_pk_mul_f32 v[224:225], v[26:27], v[46:47] op_sel_hi:[0,1]
	v_pk_mul_f32 v[234:235], v[26:27], v[46:47] op_sel:[1,0]
	v_add_f32_e32 v172, v164, v165
	v_add_f32_e32 v174, v166, v167
	v_add_f32_e32 v160, v168, v169
	v_add_f32_e32 v161, v170, v171
	s_waitcnt lgkmcnt(15)
	v_pk_fma_f32 v[218:219], v[72:73], v[12:13], v[218:219]
	v_pk_fma_f32 v[226:227], v[80:81], v[12:13], v[226:227]
	v_pk_fma_f32 v[220:221], v[74:75], v[14:15], v[220:221]
	v_pk_fma_f32 v[228:229], v[82:83], v[14:15], v[228:229]
	v_add_f32_dpp v172, v172, v172 quad_perm:[1,0,3,2] row_mask:0xf bank_mask:0xf bound_ctrl:1
	v_add_f32_dpp v174, v174, v174 quad_perm:[1,0,3,2] row_mask:0xf bank_mask:0xf bound_ctrl:1
	v_add_f32_dpp v160, v160, v160 quad_perm:[1,0,3,2] row_mask:0xf bank_mask:0xf bound_ctrl:1
	v_add_f32_dpp v161, v161, v161 quad_perm:[1,0,3,2] row_mask:0xf bank_mask:0xf bound_ctrl:1
	s_waitcnt lgkmcnt(14)
	v_pk_fma_f32 v[222:223], v[76:77], v[28:29], v[222:223]
	v_pk_fma_f32 v[230:231], v[84:85], v[28:29], v[230:231]
	v_pk_fma_f32 v[224:225], v[78:79], v[30:31], v[224:225]
	v_pk_fma_f32 v[234:235], v[86:87], v[30:31], v[234:235]
	v_add_f32_dpp v172, v172, v172 quad_perm:[2,3,0,1] row_mask:0xf bank_mask:0xf bound_ctrl:1
	v_add_f32_dpp v174, v174, v174 quad_perm:[2,3,0,1] row_mask:0xf bank_mask:0xf bound_ctrl:1
	v_add_f32_dpp v160, v160, v160 quad_perm:[2,3,0,1] row_mask:0xf bank_mask:0xf bound_ctrl:1
	v_add_f32_dpp v161, v161, v161 quad_perm:[2,3,0,1] row_mask:0xf bank_mask:0xf bound_ctrl:1
	v_add_f32_dpp v172, v172, v172 row_half_mirror row_mask:0xf bank_mask:0xf bound_ctrl:1
	v_add_f32_dpp v174, v174, v174 row_half_mirror row_mask:0xf bank_mask:0xf bound_ctrl:1
	v_add_f32_dpp v160, v160, v160 row_half_mirror row_mask:0xf bank_mask:0xf bound_ctrl:1
	v_add_f32_dpp v161, v161, v161 row_half_mirror row_mask:0xf bank_mask:0xf bound_ctrl:1
	s_waitcnt lgkmcnt(13)
	v_pk_fma_f32 v[72:73], v[32:33], v[172:173], v[218:219] op_sel_hi:[1,0,1]
	v_pk_fma_f32 v[80:81], v[32:33], v[174:175], v[226:227] op_sel_hi:[1,0,1]
	v_pk_fma_f32 v[74:75], v[34:35], v[172:173], v[220:221] op_sel_hi:[1,0,1]
	v_pk_fma_f32 v[82:83], v[34:35], v[174:175], v[228:229] op_sel_hi:[1,0,1]
	s_waitcnt lgkmcnt(12)
	v_pk_fma_f32 v[76:77], v[36:37], v[172:173], v[222:223] op_sel_hi:[1,0,1]
	v_pk_fma_f32 v[84:85], v[36:37], v[174:175], v[230:231] op_sel_hi:[1,0,1]
	v_pk_fma_f32 v[78:79], v[38:39], v[172:173], v[224:225] op_sel_hi:[1,0,1]
	v_pk_fma_f32 v[86:87], v[38:39], v[174:175], v[234:235] op_sel_hi:[1,0,1]
	s_waitcnt lgkmcnt(8)
	v_pk_mul_f32 v[164:165], v[72:73], v[176:177]
	v_pk_mul_f32 v[166:167], v[80:81], v[176:177]
	ds_read_b128 v[208:211], v2 offset:17920
	v_pk_mul_f32 v[168:169], v[72:73], v[48:49]
	v_pk_mul_f32 v[170:171], v[80:81], v[48:49]
	ds_read_b128 v[212:215], v2 offset:17936
	v_pk_fma_f32 v[164:165], v[74:75], v[178:179], v[164:165]
	v_pk_fma_f32 v[166:167], v[82:83], v[178:179], v[166:167]
	ds_read_b128 v[4:7], v2 offset:5888
	v_pk_fma_f32 v[168:169], v[74:75], v[50:51], v[168:169]
	v_pk_fma_f32 v[170:171], v[82:83], v[50:51], v[170:171]
	ds_read_b128 v[8:11], v2 offset:5904
	s_waitcnt lgkmcnt(11)
	v_pk_fma_f32 v[164:165], v[76:77], v[180:181], v[164:165]
	v_pk_fma_f32 v[166:167], v[84:85], v[180:181], v[166:167]
	ds_read_b128 v[40:43], v2 offset:14080
	v_pk_fma_f32 v[168:169], v[76:77], v[52:53], v[168:169]
	v_pk_fma_f32 v[170:171], v[84:85], v[52:53], v[170:171]
	ds_read_b128 v[44:47], v2 offset:14096
	v_pk_fma_f32 v[164:165], v[78:79], v[182:183], v[164:165]
	v_pk_fma_f32 v[166:167], v[86:87], v[182:183], v[166:167]
	ds_read_b64 v[26:27], v3 offset:42752
	v_pk_fma_f32 v[168:169], v[78:79], v[54:55], v[168:169]
	v_pk_fma_f32 v[170:171], v[86:87], v[54:55], v[170:171]
	ds_read_b128 v[12:15], v2 offset:1792
	s_waitcnt lgkmcnt(12)
	v_pk_mul_f32 v[218:219], v[216:217], v[200:201] op_sel_hi:[0,1]
	v_pk_mul_f32 v[226:227], v[216:217], v[200:201] op_sel:[1,0]
	ds_read_b128 v[28:31], v2 offset:1808
	v_pk_mul_f32 v[220:221], v[216:217], v[202:203] op_sel_hi:[0,1]
	v_pk_mul_f32 v[228:229], v[216:217], v[202:203] op_sel:[1,0]
	ds_read_b128 v[32:35], v2 offset:9984
	v_pk_mul_f32 v[222:223], v[216:217], v[204:205] op_sel_hi:[0,1]
	v_pk_mul_f32 v[230:231], v[216:217], v[204:205] op_sel:[1,0]
	ds_read_b128 v[36:39], v2 offset:10000
	v_pk_mul_f32 v[224:225], v[216:217], v[206:207] op_sel_hi:[0,1]
	v_pk_mul_f32 v[234:235], v[216:217], v[206:207] op_sel:[1,0]
	v_add_f32_e32 v172, v164, v165
	v_add_f32_e32 v174, v166, v167
	v_add_f32_e32 v244, v168, v169
	v_add_f32_e32 v245, v170, v171
	s_waitcnt lgkmcnt(14)
	v_pk_fma_f32 v[218:219], v[72:73], v[184:185], v[218:219]
	v_pk_fma_f32 v[226:227], v[80:81], v[184:185], v[226:227]
	v_pk_fma_f32 v[220:221], v[74:75], v[186:187], v[220:221]
	v_pk_fma_f32 v[228:229], v[82:83], v[186:187], v[228:229]
	v_add_f32_dpp v172, v172, v172 quad_perm:[1,0,3,2] row_mask:0xf bank_mask:0xf bound_ctrl:1
	v_add_f32_dpp v174, v174, v174 quad_perm:[1,0,3,2] row_mask:0xf bank_mask:0xf bound_ctrl:1
	v_add_f32_dpp v244, v244, v244 quad_perm:[1,0,3,2] row_mask:0xf bank_mask:0xf bound_ctrl:1
	v_add_f32_dpp v245, v245, v245 quad_perm:[1,0,3,2] row_mask:0xf bank_mask:0xf bound_ctrl:1
	s_waitcnt lgkmcnt(13)
	v_pk_fma_f32 v[222:223], v[76:77], v[188:189], v[222:223]
	v_pk_fma_f32 v[230:231], v[84:85], v[188:189], v[230:231]
	v_pk_fma_f32 v[224:225], v[78:79], v[190:191], v[224:225]
	v_pk_fma_f32 v[234:235], v[86:87], v[190:191], v[234:235]
	v_add_f32_dpp v172, v172, v172 quad_perm:[2,3,0,1] row_mask:0xf bank_mask:0xf bound_ctrl:1
	v_add_f32_dpp v174, v174, v174 quad_perm:[2,3,0,1] row_mask:0xf bank_mask:0xf bound_ctrl:1
	v_add_f32_dpp v244, v244, v244 quad_perm:[2,3,0,1] row_mask:0xf bank_mask:0xf bound_ctrl:1
	v_add_f32_dpp v245, v245, v245 quad_perm:[2,3,0,1] row_mask:0xf bank_mask:0xf bound_ctrl:1
	v_add_f32_dpp v172, v172, v172 row_half_mirror row_mask:0xf bank_mask:0xf bound_ctrl:1
	v_add_f32_dpp v174, v174, v174 row_half_mirror row_mask:0xf bank_mask:0xf bound_ctrl:1
	v_add_f32_dpp v244, v244, v244 row_half_mirror row_mask:0xf bank_mask:0xf bound_ctrl:1
	v_add_f32_dpp v245, v245, v245 row_half_mirror row_mask:0xf bank_mask:0xf bound_ctrl:1
	s_waitcnt lgkmcnt(12)
	v_pk_fma_f32 v[72:73], v[192:193], v[172:173], v[218:219] op_sel_hi:[1,0,1]
	v_pk_fma_f32 v[80:81], v[192:193], v[174:175], v[226:227] op_sel_hi:[1,0,1]
	v_pk_fma_f32 v[74:75], v[194:195], v[172:173], v[220:221] op_sel_hi:[1,0,1]
	v_pk_fma_f32 v[82:83], v[194:195], v[174:175], v[228:229] op_sel_hi:[1,0,1]
	s_waitcnt lgkmcnt(11)
	v_pk_fma_f32 v[76:77], v[196:197], v[172:173], v[222:223] op_sel_hi:[1,0,1]
	v_pk_fma_f32 v[84:85], v[196:197], v[174:175], v[230:231] op_sel_hi:[1,0,1]
	v_pk_fma_f32 v[78:79], v[198:199], v[172:173], v[224:225] op_sel_hi:[1,0,1]
	v_pk_fma_f32 v[86:87], v[198:199], v[174:175], v[234:235] op_sel_hi:[1,0,1]
	ds_write2_b64 v246, v[160:161], v[244:245] offset0:128 offset1:160
	s_waitcnt lgkmcnt(9)
	v_pk_mul_f32 v[164:165], v[72:73], v[4:5]
	v_pk_mul_f32 v[166:167], v[80:81], v[4:5]
	ds_read_b128 v[48:51], v2 offset:18176
	v_pk_mul_f32 v[168:169], v[72:73], v[208:209]
	v_pk_mul_f32 v[170:171], v[80:81], v[208:209]
	ds_read_b128 v[52:55], v2 offset:18192
	v_pk_fma_f32 v[164:165], v[74:75], v[6:7], v[164:165]
	v_pk_fma_f32 v[166:167], v[82:83], v[6:7], v[166:167]
	ds_read_b128 v[176:179], v2 offset:6144
	v_pk_fma_f32 v[168:169], v[74:75], v[210:211], v[168:169]
	v_pk_fma_f32 v[170:171], v[82:83], v[210:211], v[170:171]
	ds_read_b128 v[180:183], v2 offset:6160
	s_waitcnt lgkmcnt(12)
	v_pk_fma_f32 v[164:165], v[76:77], v[8:9], v[164:165]
	v_pk_fma_f32 v[166:167], v[84:85], v[8:9], v[166:167]
	ds_read_b128 v[200:203], v2 offset:14336
	v_pk_fma_f32 v[168:169], v[76:77], v[212:213], v[168:169]
	v_pk_fma_f32 v[170:171], v[84:85], v[212:213], v[170:171]
	ds_read_b128 v[204:207], v2 offset:14352
	v_pk_fma_f32 v[164:165], v[78:79], v[10:11], v[164:165]
	v_pk_fma_f32 v[166:167], v[86:87], v[10:11], v[166:167]
	ds_read_b64 v[216:217], v3 offset:43008
	v_pk_fma_f32 v[168:169], v[78:79], v[214:215], v[168:169]
	v_pk_fma_f32 v[170:171], v[86:87], v[214:215], v[170:171]
	ds_read_b128 v[184:187], v2 offset:2048
	s_waitcnt lgkmcnt(13)
	v_pk_mul_f32 v[218:219], v[26:27], v[40:41] op_sel_hi:[0,1]
	v_pk_mul_f32 v[226:227], v[26:27], v[40:41] op_sel:[1,0]
	ds_read_b128 v[188:191], v2 offset:2064
	v_pk_mul_f32 v[220:221], v[26:27], v[42:43] op_sel_hi:[0,1]
	v_pk_mul_f32 v[228:229], v[26:27], v[42:43] op_sel:[1,0]
	ds_read_b128 v[192:195], v2 offset:10240
	v_pk_mul_f32 v[222:223], v[26:27], v[44:45] op_sel_hi:[0,1]
	v_pk_mul_f32 v[230:231], v[26:27], v[44:45] op_sel:[1,0]
	ds_read_b128 v[196:199], v2 offset:10256
	v_pk_mul_f32 v[224:225], v[26:27], v[46:47] op_sel_hi:[0,1]
	v_pk_mul_f32 v[234:235], v[26:27], v[46:47] op_sel:[1,0]
	v_add_f32_e32 v172, v164, v165
	v_add_f32_e32 v174, v166, v167
	v_add_f32_e32 v160, v168, v169
	v_add_f32_e32 v161, v170, v171
	s_waitcnt lgkmcnt(15)
	v_pk_fma_f32 v[218:219], v[72:73], v[12:13], v[218:219]
	v_pk_fma_f32 v[226:227], v[80:81], v[12:13], v[226:227]
	v_pk_fma_f32 v[220:221], v[74:75], v[14:15], v[220:221]
	v_pk_fma_f32 v[228:229], v[82:83], v[14:15], v[228:229]
	v_add_f32_dpp v172, v172, v172 quad_perm:[1,0,3,2] row_mask:0xf bank_mask:0xf bound_ctrl:1
	v_add_f32_dpp v174, v174, v174 quad_perm:[1,0,3,2] row_mask:0xf bank_mask:0xf bound_ctrl:1
	v_add_f32_dpp v160, v160, v160 quad_perm:[1,0,3,2] row_mask:0xf bank_mask:0xf bound_ctrl:1
	v_add_f32_dpp v161, v161, v161 quad_perm:[1,0,3,2] row_mask:0xf bank_mask:0xf bound_ctrl:1
	s_waitcnt lgkmcnt(14)
	v_pk_fma_f32 v[222:223], v[76:77], v[28:29], v[222:223]
	v_pk_fma_f32 v[230:231], v[84:85], v[28:29], v[230:231]
	v_pk_fma_f32 v[224:225], v[78:79], v[30:31], v[224:225]
	v_pk_fma_f32 v[234:235], v[86:87], v[30:31], v[234:235]
	v_add_f32_dpp v172, v172, v172 quad_perm:[2,3,0,1] row_mask:0xf bank_mask:0xf bound_ctrl:1
	v_add_f32_dpp v174, v174, v174 quad_perm:[2,3,0,1] row_mask:0xf bank_mask:0xf bound_ctrl:1
	v_add_f32_dpp v160, v160, v160 quad_perm:[2,3,0,1] row_mask:0xf bank_mask:0xf bound_ctrl:1
	v_add_f32_dpp v161, v161, v161 quad_perm:[2,3,0,1] row_mask:0xf bank_mask:0xf bound_ctrl:1
	v_add_f32_dpp v172, v172, v172 row_half_mirror row_mask:0xf bank_mask:0xf bound_ctrl:1
	v_add_f32_dpp v174, v174, v174 row_half_mirror row_mask:0xf bank_mask:0xf bound_ctrl:1
	v_add_f32_dpp v160, v160, v160 row_half_mirror row_mask:0xf bank_mask:0xf bound_ctrl:1
	v_add_f32_dpp v161, v161, v161 row_half_mirror row_mask:0xf bank_mask:0xf bound_ctrl:1
	s_waitcnt lgkmcnt(13)
	v_pk_fma_f32 v[72:73], v[32:33], v[172:173], v[218:219] op_sel_hi:[1,0,1]
	v_pk_fma_f32 v[80:81], v[32:33], v[174:175], v[226:227] op_sel_hi:[1,0,1]
	v_pk_fma_f32 v[74:75], v[34:35], v[172:173], v[220:221] op_sel_hi:[1,0,1]
	v_pk_fma_f32 v[82:83], v[34:35], v[174:175], v[228:229] op_sel_hi:[1,0,1]
	s_waitcnt lgkmcnt(12)
	v_pk_fma_f32 v[76:77], v[36:37], v[172:173], v[222:223] op_sel_hi:[1,0,1]
	v_pk_fma_f32 v[84:85], v[36:37], v[174:175], v[230:231] op_sel_hi:[1,0,1]
	v_pk_fma_f32 v[78:79], v[38:39], v[172:173], v[224:225] op_sel_hi:[1,0,1]
	v_pk_fma_f32 v[86:87], v[38:39], v[174:175], v[234:235] op_sel_hi:[1,0,1]
	s_waitcnt lgkmcnt(8)
	v_pk_mul_f32 v[164:165], v[72:73], v[176:177]
	v_pk_mul_f32 v[166:167], v[80:81], v[176:177]
	ds_read_b128 v[208:211], v2 offset:18432
	v_pk_mul_f32 v[168:169], v[72:73], v[48:49]
	v_pk_mul_f32 v[170:171], v[80:81], v[48:49]
	ds_read_b128 v[212:215], v2 offset:18448
	v_pk_fma_f32 v[164:165], v[74:75], v[178:179], v[164:165]
	v_pk_fma_f32 v[166:167], v[82:83], v[178:179], v[166:167]
	ds_read_b128 v[4:7], v2 offset:6400
	v_pk_fma_f32 v[168:169], v[74:75], v[50:51], v[168:169]
	v_pk_fma_f32 v[170:171], v[82:83], v[50:51], v[170:171]
	ds_read_b128 v[8:11], v2 offset:6416
	s_waitcnt lgkmcnt(11)
	v_pk_fma_f32 v[164:165], v[76:77], v[180:181], v[164:165]
	v_pk_fma_f32 v[166:167], v[84:85], v[180:181], v[166:167]
	ds_read_b128 v[40:43], v2 offset:14592
	v_pk_fma_f32 v[168:169], v[76:77], v[52:53], v[168:169]
	v_pk_fma_f32 v[170:171], v[84:85], v[52:53], v[170:171]
	ds_read_b128 v[44:47], v2 offset:14608
	v_pk_fma_f32 v[164:165], v[78:79], v[182:183], v[164:165]
	v_pk_fma_f32 v[166:167], v[86:87], v[182:183], v[166:167]
	ds_read_b64 v[26:27], v3 offset:43264
	v_pk_fma_f32 v[168:169], v[78:79], v[54:55], v[168:169]
	v_pk_fma_f32 v[170:171], v[86:87], v[54:55], v[170:171]
	ds_read_b128 v[12:15], v2 offset:2304
	s_waitcnt lgkmcnt(12)
	v_pk_mul_f32 v[218:219], v[216:217], v[200:201] op_sel_hi:[0,1]
	v_pk_mul_f32 v[226:227], v[216:217], v[200:201] op_sel:[1,0]
	ds_read_b128 v[28:31], v2 offset:2320
	v_pk_mul_f32 v[220:221], v[216:217], v[202:203] op_sel_hi:[0,1]
	v_pk_mul_f32 v[228:229], v[216:217], v[202:203] op_sel:[1,0]
	ds_read_b128 v[32:35], v2 offset:10496
	v_pk_mul_f32 v[222:223], v[216:217], v[204:205] op_sel_hi:[0,1]
	v_pk_mul_f32 v[230:231], v[216:217], v[204:205] op_sel:[1,0]
	ds_read_b128 v[36:39], v2 offset:10512
	v_pk_mul_f32 v[224:225], v[216:217], v[206:207] op_sel_hi:[0,1]
	v_pk_mul_f32 v[234:235], v[216:217], v[206:207] op_sel:[1,0]
	v_add_f32_e32 v172, v164, v165
	v_add_f32_e32 v174, v166, v167
	v_add_f32_e32 v244, v168, v169
	v_add_f32_e32 v245, v170, v171
	s_waitcnt lgkmcnt(14)
	v_pk_fma_f32 v[218:219], v[72:73], v[184:185], v[218:219]
	v_pk_fma_f32 v[226:227], v[80:81], v[184:185], v[226:227]
	v_pk_fma_f32 v[220:221], v[74:75], v[186:187], v[220:221]
	v_pk_fma_f32 v[228:229], v[82:83], v[186:187], v[228:229]
	v_add_f32_dpp v172, v172, v172 quad_perm:[1,0,3,2] row_mask:0xf bank_mask:0xf bound_ctrl:1
	v_add_f32_dpp v174, v174, v174 quad_perm:[1,0,3,2] row_mask:0xf bank_mask:0xf bound_ctrl:1
	v_add_f32_dpp v244, v244, v244 quad_perm:[1,0,3,2] row_mask:0xf bank_mask:0xf bound_ctrl:1
	v_add_f32_dpp v245, v245, v245 quad_perm:[1,0,3,2] row_mask:0xf bank_mask:0xf bound_ctrl:1
	s_waitcnt lgkmcnt(13)
	v_pk_fma_f32 v[222:223], v[76:77], v[188:189], v[222:223]
	v_pk_fma_f32 v[230:231], v[84:85], v[188:189], v[230:231]
	v_pk_fma_f32 v[224:225], v[78:79], v[190:191], v[224:225]
	v_pk_fma_f32 v[234:235], v[86:87], v[190:191], v[234:235]
	v_add_f32_dpp v172, v172, v172 quad_perm:[2,3,0,1] row_mask:0xf bank_mask:0xf bound_ctrl:1
	v_add_f32_dpp v174, v174, v174 quad_perm:[2,3,0,1] row_mask:0xf bank_mask:0xf bound_ctrl:1
	v_add_f32_dpp v244, v244, v244 quad_perm:[2,3,0,1] row_mask:0xf bank_mask:0xf bound_ctrl:1
	v_add_f32_dpp v245, v245, v245 quad_perm:[2,3,0,1] row_mask:0xf bank_mask:0xf bound_ctrl:1
	v_add_f32_dpp v172, v172, v172 row_half_mirror row_mask:0xf bank_mask:0xf bound_ctrl:1
	v_add_f32_dpp v174, v174, v174 row_half_mirror row_mask:0xf bank_mask:0xf bound_ctrl:1
	v_add_f32_dpp v244, v244, v244 row_half_mirror row_mask:0xf bank_mask:0xf bound_ctrl:1
	v_add_f32_dpp v245, v245, v245 row_half_mirror row_mask:0xf bank_mask:0xf bound_ctrl:1
	s_waitcnt lgkmcnt(12)
	v_pk_fma_f32 v[72:73], v[192:193], v[172:173], v[218:219] op_sel_hi:[1,0,1]
	v_pk_fma_f32 v[80:81], v[192:193], v[174:175], v[226:227] op_sel_hi:[1,0,1]
	v_pk_fma_f32 v[74:75], v[194:195], v[172:173], v[220:221] op_sel_hi:[1,0,1]
	v_pk_fma_f32 v[82:83], v[194:195], v[174:175], v[228:229] op_sel_hi:[1,0,1]
	s_waitcnt lgkmcnt(11)
	v_pk_fma_f32 v[76:77], v[196:197], v[172:173], v[222:223] op_sel_hi:[1,0,1]
	v_pk_fma_f32 v[84:85], v[196:197], v[174:175], v[230:231] op_sel_hi:[1,0,1]
	v_pk_fma_f32 v[78:79], v[198:199], v[172:173], v[224:225] op_sel_hi:[1,0,1]
	v_pk_fma_f32 v[86:87], v[198:199], v[174:175], v[234:235] op_sel_hi:[1,0,1]
	ds_write2_b64 v246, v[160:161], v[244:245] offset0:192 offset1:224
	s_waitcnt lgkmcnt(9)
	v_pk_mul_f32 v[164:165], v[72:73], v[4:5]
	v_pk_mul_f32 v[166:167], v[80:81], v[4:5]
	ds_read_b128 v[48:51], v2 offset:18688
	v_pk_mul_f32 v[168:169], v[72:73], v[208:209]
	v_pk_mul_f32 v[170:171], v[80:81], v[208:209]
	ds_read_b128 v[52:55], v2 offset:18704
	v_pk_fma_f32 v[164:165], v[74:75], v[6:7], v[164:165]
	v_pk_fma_f32 v[166:167], v[82:83], v[6:7], v[166:167]
	ds_read_b128 v[176:179], v2 offset:6656
	v_pk_fma_f32 v[168:169], v[74:75], v[210:211], v[168:169]
	v_pk_fma_f32 v[170:171], v[82:83], v[210:211], v[170:171]
	ds_read_b128 v[180:183], v2 offset:6672
	s_waitcnt lgkmcnt(12)
	v_pk_fma_f32 v[164:165], v[76:77], v[8:9], v[164:165]
	v_pk_fma_f32 v[166:167], v[84:85], v[8:9], v[166:167]
	ds_read_b128 v[200:203], v2 offset:14848
	v_pk_fma_f32 v[168:169], v[76:77], v[212:213], v[168:169]
	v_pk_fma_f32 v[170:171], v[84:85], v[212:213], v[170:171]
	ds_read_b128 v[204:207], v2 offset:14864
	v_pk_fma_f32 v[164:165], v[78:79], v[10:11], v[164:165]
	v_pk_fma_f32 v[166:167], v[86:87], v[10:11], v[166:167]
	ds_read_b64 v[216:217], v3 offset:43520
	v_pk_fma_f32 v[168:169], v[78:79], v[214:215], v[168:169]
	v_pk_fma_f32 v[170:171], v[86:87], v[214:215], v[170:171]
	ds_read_b128 v[184:187], v2 offset:2560
	s_waitcnt lgkmcnt(13)
	v_pk_mul_f32 v[218:219], v[26:27], v[40:41] op_sel_hi:[0,1]
	v_pk_mul_f32 v[226:227], v[26:27], v[40:41] op_sel:[1,0]
	ds_read_b128 v[188:191], v2 offset:2576
	v_pk_mul_f32 v[220:221], v[26:27], v[42:43] op_sel_hi:[0,1]
	v_pk_mul_f32 v[228:229], v[26:27], v[42:43] op_sel:[1,0]
	ds_read_b128 v[192:195], v2 offset:10752
	v_pk_mul_f32 v[222:223], v[26:27], v[44:45] op_sel_hi:[0,1]
	v_pk_mul_f32 v[230:231], v[26:27], v[44:45] op_sel:[1,0]
	ds_read_b128 v[196:199], v2 offset:10768
	v_pk_mul_f32 v[224:225], v[26:27], v[46:47] op_sel_hi:[0,1]
	v_pk_mul_f32 v[234:235], v[26:27], v[46:47] op_sel:[1,0]
	v_add_f32_e32 v172, v164, v165
	v_add_f32_e32 v174, v166, v167
	v_add_f32_e32 v160, v168, v169
	v_add_f32_e32 v161, v170, v171
	s_waitcnt lgkmcnt(15)
	v_pk_fma_f32 v[218:219], v[72:73], v[12:13], v[218:219]
	v_pk_fma_f32 v[226:227], v[80:81], v[12:13], v[226:227]
	v_pk_fma_f32 v[220:221], v[74:75], v[14:15], v[220:221]
	v_pk_fma_f32 v[228:229], v[82:83], v[14:15], v[228:229]
	v_add_f32_dpp v172, v172, v172 quad_perm:[1,0,3,2] row_mask:0xf bank_mask:0xf bound_ctrl:1
	v_add_f32_dpp v174, v174, v174 quad_perm:[1,0,3,2] row_mask:0xf bank_mask:0xf bound_ctrl:1
	v_add_f32_dpp v160, v160, v160 quad_perm:[1,0,3,2] row_mask:0xf bank_mask:0xf bound_ctrl:1
	v_add_f32_dpp v161, v161, v161 quad_perm:[1,0,3,2] row_mask:0xf bank_mask:0xf bound_ctrl:1
	s_waitcnt lgkmcnt(14)
	v_pk_fma_f32 v[222:223], v[76:77], v[28:29], v[222:223]
	v_pk_fma_f32 v[230:231], v[84:85], v[28:29], v[230:231]
	v_pk_fma_f32 v[224:225], v[78:79], v[30:31], v[224:225]
	v_pk_fma_f32 v[234:235], v[86:87], v[30:31], v[234:235]
	v_add_f32_dpp v172, v172, v172 quad_perm:[2,3,0,1] row_mask:0xf bank_mask:0xf bound_ctrl:1
	v_add_f32_dpp v174, v174, v174 quad_perm:[2,3,0,1] row_mask:0xf bank_mask:0xf bound_ctrl:1
	v_add_f32_dpp v160, v160, v160 quad_perm:[2,3,0,1] row_mask:0xf bank_mask:0xf bound_ctrl:1
	v_add_f32_dpp v161, v161, v161 quad_perm:[2,3,0,1] row_mask:0xf bank_mask:0xf bound_ctrl:1
	v_add_f32_dpp v172, v172, v172 row_half_mirror row_mask:0xf bank_mask:0xf bound_ctrl:1
	v_add_f32_dpp v174, v174, v174 row_half_mirror row_mask:0xf bank_mask:0xf bound_ctrl:1
	v_add_f32_dpp v160, v160, v160 row_half_mirror row_mask:0xf bank_mask:0xf bound_ctrl:1
	v_add_f32_dpp v161, v161, v161 row_half_mirror row_mask:0xf bank_mask:0xf bound_ctrl:1
	s_waitcnt lgkmcnt(13)
	v_pk_fma_f32 v[72:73], v[32:33], v[172:173], v[218:219] op_sel_hi:[1,0,1]
	v_pk_fma_f32 v[80:81], v[32:33], v[174:175], v[226:227] op_sel_hi:[1,0,1]
	v_pk_fma_f32 v[74:75], v[34:35], v[172:173], v[220:221] op_sel_hi:[1,0,1]
	v_pk_fma_f32 v[82:83], v[34:35], v[174:175], v[228:229] op_sel_hi:[1,0,1]
	s_waitcnt lgkmcnt(12)
	v_pk_fma_f32 v[76:77], v[36:37], v[172:173], v[222:223] op_sel_hi:[1,0,1]
	v_pk_fma_f32 v[84:85], v[36:37], v[174:175], v[230:231] op_sel_hi:[1,0,1]
	v_pk_fma_f32 v[78:79], v[38:39], v[172:173], v[224:225] op_sel_hi:[1,0,1]
	v_pk_fma_f32 v[86:87], v[38:39], v[174:175], v[234:235] op_sel_hi:[1,0,1]
	s_waitcnt lgkmcnt(8)
	v_pk_mul_f32 v[164:165], v[72:73], v[176:177]
	v_pk_mul_f32 v[166:167], v[80:81], v[176:177]
	ds_read_b128 v[208:211], v2 offset:18944
	v_pk_mul_f32 v[168:169], v[72:73], v[48:49]
	v_pk_mul_f32 v[170:171], v[80:81], v[48:49]
	ds_read_b128 v[212:215], v2 offset:18960
	v_pk_fma_f32 v[164:165], v[74:75], v[178:179], v[164:165]
	v_pk_fma_f32 v[166:167], v[82:83], v[178:179], v[166:167]
	ds_read_b128 v[4:7], v2 offset:6912
	v_pk_fma_f32 v[168:169], v[74:75], v[50:51], v[168:169]
	v_pk_fma_f32 v[170:171], v[82:83], v[50:51], v[170:171]
	ds_read_b128 v[8:11], v2 offset:6928
	s_waitcnt lgkmcnt(11)
	v_pk_fma_f32 v[164:165], v[76:77], v[180:181], v[164:165]
	v_pk_fma_f32 v[166:167], v[84:85], v[180:181], v[166:167]
	ds_read_b128 v[40:43], v2 offset:15104
	v_pk_fma_f32 v[168:169], v[76:77], v[52:53], v[168:169]
	v_pk_fma_f32 v[170:171], v[84:85], v[52:53], v[170:171]
	ds_read_b128 v[44:47], v2 offset:15120
	v_pk_fma_f32 v[164:165], v[78:79], v[182:183], v[164:165]
	v_pk_fma_f32 v[166:167], v[86:87], v[182:183], v[166:167]
	ds_read_b64 v[26:27], v3 offset:43776
	v_pk_fma_f32 v[168:169], v[78:79], v[54:55], v[168:169]
	v_pk_fma_f32 v[170:171], v[86:87], v[54:55], v[170:171]
	ds_read_b128 v[12:15], v2 offset:2816
	s_waitcnt lgkmcnt(12)
	v_pk_mul_f32 v[218:219], v[216:217], v[200:201] op_sel_hi:[0,1]
	v_pk_mul_f32 v[226:227], v[216:217], v[200:201] op_sel:[1,0]
	ds_read_b128 v[28:31], v2 offset:2832
	v_pk_mul_f32 v[220:221], v[216:217], v[202:203] op_sel_hi:[0,1]
	v_pk_mul_f32 v[228:229], v[216:217], v[202:203] op_sel:[1,0]
	ds_read_b128 v[32:35], v2 offset:11008
	v_pk_mul_f32 v[222:223], v[216:217], v[204:205] op_sel_hi:[0,1]
	v_pk_mul_f32 v[230:231], v[216:217], v[204:205] op_sel:[1,0]
	ds_read_b128 v[36:39], v2 offset:11024
	v_pk_mul_f32 v[224:225], v[216:217], v[206:207] op_sel_hi:[0,1]
	v_pk_mul_f32 v[234:235], v[216:217], v[206:207] op_sel:[1,0]
	v_add_f32_e32 v172, v164, v165
	v_add_f32_e32 v174, v166, v167
	v_add_f32_e32 v244, v168, v169
	v_add_f32_e32 v245, v170, v171
	s_waitcnt lgkmcnt(14)
	v_pk_fma_f32 v[218:219], v[72:73], v[184:185], v[218:219]
	v_pk_fma_f32 v[226:227], v[80:81], v[184:185], v[226:227]
	v_pk_fma_f32 v[220:221], v[74:75], v[186:187], v[220:221]
	v_pk_fma_f32 v[228:229], v[82:83], v[186:187], v[228:229]
	v_add_f32_dpp v172, v172, v172 quad_perm:[1,0,3,2] row_mask:0xf bank_mask:0xf bound_ctrl:1
	v_add_f32_dpp v174, v174, v174 quad_perm:[1,0,3,2] row_mask:0xf bank_mask:0xf bound_ctrl:1
	v_add_f32_dpp v244, v244, v244 quad_perm:[1,0,3,2] row_mask:0xf bank_mask:0xf bound_ctrl:1
	v_add_f32_dpp v245, v245, v245 quad_perm:[1,0,3,2] row_mask:0xf bank_mask:0xf bound_ctrl:1
	s_waitcnt lgkmcnt(13)
	v_pk_fma_f32 v[222:223], v[76:77], v[188:189], v[222:223]
	v_pk_fma_f32 v[230:231], v[84:85], v[188:189], v[230:231]
	v_pk_fma_f32 v[224:225], v[78:79], v[190:191], v[224:225]
	v_pk_fma_f32 v[234:235], v[86:87], v[190:191], v[234:235]
	v_add_f32_dpp v172, v172, v172 quad_perm:[2,3,0,1] row_mask:0xf bank_mask:0xf bound_ctrl:1
	v_add_f32_dpp v174, v174, v174 quad_perm:[2,3,0,1] row_mask:0xf bank_mask:0xf bound_ctrl:1
	v_add_f32_dpp v244, v244, v244 quad_perm:[2,3,0,1] row_mask:0xf bank_mask:0xf bound_ctrl:1
	v_add_f32_dpp v245, v245, v245 quad_perm:[2,3,0,1] row_mask:0xf bank_mask:0xf bound_ctrl:1
	v_add_f32_dpp v172, v172, v172 row_half_mirror row_mask:0xf bank_mask:0xf bound_ctrl:1
	v_add_f32_dpp v174, v174, v174 row_half_mirror row_mask:0xf bank_mask:0xf bound_ctrl:1
	v_add_f32_dpp v244, v244, v244 row_half_mirror row_mask:0xf bank_mask:0xf bound_ctrl:1
	v_add_f32_dpp v245, v245, v245 row_half_mirror row_mask:0xf bank_mask:0xf bound_ctrl:1
	s_waitcnt lgkmcnt(12)
	v_pk_fma_f32 v[72:73], v[192:193], v[172:173], v[218:219] op_sel_hi:[1,0,1]
	v_pk_fma_f32 v[80:81], v[192:193], v[174:175], v[226:227] op_sel_hi:[1,0,1]
	v_pk_fma_f32 v[74:75], v[194:195], v[172:173], v[220:221] op_sel_hi:[1,0,1]
	v_pk_fma_f32 v[82:83], v[194:195], v[174:175], v[228:229] op_sel_hi:[1,0,1]
	s_waitcnt lgkmcnt(11)
	v_pk_fma_f32 v[76:77], v[196:197], v[172:173], v[222:223] op_sel_hi:[1,0,1]
	v_pk_fma_f32 v[84:85], v[196:197], v[174:175], v[230:231] op_sel_hi:[1,0,1]
	v_pk_fma_f32 v[78:79], v[198:199], v[172:173], v[224:225] op_sel_hi:[1,0,1]
	v_pk_fma_f32 v[86:87], v[198:199], v[174:175], v[234:235] op_sel_hi:[1,0,1]
	ds_write2_b64 v247, v[160:161], v[244:245] offset1:32
	s_waitcnt lgkmcnt(9)
	v_pk_mul_f32 v[164:165], v[72:73], v[4:5]
	v_pk_mul_f32 v[166:167], v[80:81], v[4:5]
	ds_read_b128 v[48:51], v2 offset:19200
	v_pk_mul_f32 v[168:169], v[72:73], v[208:209]
	v_pk_mul_f32 v[170:171], v[80:81], v[208:209]
	ds_read_b128 v[52:55], v2 offset:19216
	v_pk_fma_f32 v[164:165], v[74:75], v[6:7], v[164:165]
	v_pk_fma_f32 v[166:167], v[82:83], v[6:7], v[166:167]
	ds_read_b128 v[176:179], v2 offset:7168
	v_pk_fma_f32 v[168:169], v[74:75], v[210:211], v[168:169]
	v_pk_fma_f32 v[170:171], v[82:83], v[210:211], v[170:171]
	ds_read_b128 v[180:183], v2 offset:7184
	s_waitcnt lgkmcnt(12)
	v_pk_fma_f32 v[164:165], v[76:77], v[8:9], v[164:165]
	v_pk_fma_f32 v[166:167], v[84:85], v[8:9], v[166:167]
	ds_read_b128 v[200:203], v2 offset:15360
	v_pk_fma_f32 v[168:169], v[76:77], v[212:213], v[168:169]
	v_pk_fma_f32 v[170:171], v[84:85], v[212:213], v[170:171]
	ds_read_b128 v[204:207], v2 offset:15376
	v_pk_fma_f32 v[164:165], v[78:79], v[10:11], v[164:165]
	v_pk_fma_f32 v[166:167], v[86:87], v[10:11], v[166:167]
	ds_read_b64 v[216:217], v3 offset:44032
	v_pk_fma_f32 v[168:169], v[78:79], v[214:215], v[168:169]
	v_pk_fma_f32 v[170:171], v[86:87], v[214:215], v[170:171]
	ds_read_b128 v[184:187], v2 offset:3072
	s_waitcnt lgkmcnt(13)
	v_pk_mul_f32 v[218:219], v[26:27], v[40:41] op_sel_hi:[0,1]
	v_pk_mul_f32 v[226:227], v[26:27], v[40:41] op_sel:[1,0]
	ds_read_b128 v[188:191], v2 offset:3088
	v_pk_mul_f32 v[220:221], v[26:27], v[42:43] op_sel_hi:[0,1]
	v_pk_mul_f32 v[228:229], v[26:27], v[42:43] op_sel:[1,0]
	ds_read_b128 v[192:195], v2 offset:11264
	v_pk_mul_f32 v[222:223], v[26:27], v[44:45] op_sel_hi:[0,1]
	v_pk_mul_f32 v[230:231], v[26:27], v[44:45] op_sel:[1,0]
	ds_read_b128 v[196:199], v2 offset:11280
	v_pk_mul_f32 v[224:225], v[26:27], v[46:47] op_sel_hi:[0,1]
	v_pk_mul_f32 v[234:235], v[26:27], v[46:47] op_sel:[1,0]
	v_add_f32_e32 v172, v164, v165
	v_add_f32_e32 v174, v166, v167
	v_add_f32_e32 v160, v168, v169
	v_add_f32_e32 v161, v170, v171
	s_waitcnt lgkmcnt(15)
	v_pk_fma_f32 v[218:219], v[72:73], v[12:13], v[218:219]
	v_pk_fma_f32 v[226:227], v[80:81], v[12:13], v[226:227]
	v_pk_fma_f32 v[220:221], v[74:75], v[14:15], v[220:221]
	v_pk_fma_f32 v[228:229], v[82:83], v[14:15], v[228:229]
	v_add_f32_dpp v172, v172, v172 quad_perm:[1,0,3,2] row_mask:0xf bank_mask:0xf bound_ctrl:1
	v_add_f32_dpp v174, v174, v174 quad_perm:[1,0,3,2] row_mask:0xf bank_mask:0xf bound_ctrl:1
	v_add_f32_dpp v160, v160, v160 quad_perm:[1,0,3,2] row_mask:0xf bank_mask:0xf bound_ctrl:1
	v_add_f32_dpp v161, v161, v161 quad_perm:[1,0,3,2] row_mask:0xf bank_mask:0xf bound_ctrl:1
	s_waitcnt lgkmcnt(14)
	v_pk_fma_f32 v[222:223], v[76:77], v[28:29], v[222:223]
	v_pk_fma_f32 v[230:231], v[84:85], v[28:29], v[230:231]
	v_pk_fma_f32 v[224:225], v[78:79], v[30:31], v[224:225]
	v_pk_fma_f32 v[234:235], v[86:87], v[30:31], v[234:235]
	v_add_f32_dpp v172, v172, v172 quad_perm:[2,3,0,1] row_mask:0xf bank_mask:0xf bound_ctrl:1
	v_add_f32_dpp v174, v174, v174 quad_perm:[2,3,0,1] row_mask:0xf bank_mask:0xf bound_ctrl:1
	v_add_f32_dpp v160, v160, v160 quad_perm:[2,3,0,1] row_mask:0xf bank_mask:0xf bound_ctrl:1
	v_add_f32_dpp v161, v161, v161 quad_perm:[2,3,0,1] row_mask:0xf bank_mask:0xf bound_ctrl:1
	v_add_f32_dpp v172, v172, v172 row_half_mirror row_mask:0xf bank_mask:0xf bound_ctrl:1
	v_add_f32_dpp v174, v174, v174 row_half_mirror row_mask:0xf bank_mask:0xf bound_ctrl:1
	v_add_f32_dpp v160, v160, v160 row_half_mirror row_mask:0xf bank_mask:0xf bound_ctrl:1
	v_add_f32_dpp v161, v161, v161 row_half_mirror row_mask:0xf bank_mask:0xf bound_ctrl:1
	s_waitcnt lgkmcnt(13)
	v_pk_fma_f32 v[72:73], v[32:33], v[172:173], v[218:219] op_sel_hi:[1,0,1]
	v_pk_fma_f32 v[80:81], v[32:33], v[174:175], v[226:227] op_sel_hi:[1,0,1]
	v_pk_fma_f32 v[74:75], v[34:35], v[172:173], v[220:221] op_sel_hi:[1,0,1]
	v_pk_fma_f32 v[82:83], v[34:35], v[174:175], v[228:229] op_sel_hi:[1,0,1]
	s_waitcnt lgkmcnt(12)
	v_pk_fma_f32 v[76:77], v[36:37], v[172:173], v[222:223] op_sel_hi:[1,0,1]
	v_pk_fma_f32 v[84:85], v[36:37], v[174:175], v[230:231] op_sel_hi:[1,0,1]
	v_pk_fma_f32 v[78:79], v[38:39], v[172:173], v[224:225] op_sel_hi:[1,0,1]
	v_pk_fma_f32 v[86:87], v[38:39], v[174:175], v[234:235] op_sel_hi:[1,0,1]
	s_waitcnt lgkmcnt(8)
	v_pk_mul_f32 v[164:165], v[72:73], v[176:177]
	v_pk_mul_f32 v[166:167], v[80:81], v[176:177]
	ds_read_b128 v[208:211], v2 offset:19456
	v_pk_mul_f32 v[168:169], v[72:73], v[48:49]
	v_pk_mul_f32 v[170:171], v[80:81], v[48:49]
	ds_read_b128 v[212:215], v2 offset:19472
	v_pk_fma_f32 v[164:165], v[74:75], v[178:179], v[164:165]
	v_pk_fma_f32 v[166:167], v[82:83], v[178:179], v[166:167]
	ds_read_b128 v[4:7], v2 offset:7424
	v_pk_fma_f32 v[168:169], v[74:75], v[50:51], v[168:169]
	v_pk_fma_f32 v[170:171], v[82:83], v[50:51], v[170:171]
	ds_read_b128 v[8:11], v2 offset:7440
	s_waitcnt lgkmcnt(11)
	v_pk_fma_f32 v[164:165], v[76:77], v[180:181], v[164:165]
	v_pk_fma_f32 v[166:167], v[84:85], v[180:181], v[166:167]
	ds_read_b128 v[40:43], v2 offset:15616
	v_pk_fma_f32 v[168:169], v[76:77], v[52:53], v[168:169]
	v_pk_fma_f32 v[170:171], v[84:85], v[52:53], v[170:171]
	ds_read_b128 v[44:47], v2 offset:15632
	v_pk_fma_f32 v[164:165], v[78:79], v[182:183], v[164:165]
	v_pk_fma_f32 v[166:167], v[86:87], v[182:183], v[166:167]
	ds_read_b64 v[26:27], v3 offset:44288
	v_pk_fma_f32 v[168:169], v[78:79], v[54:55], v[168:169]
	v_pk_fma_f32 v[170:171], v[86:87], v[54:55], v[170:171]
	ds_read_b128 v[12:15], v2 offset:3328
	s_waitcnt lgkmcnt(12)
	v_pk_mul_f32 v[218:219], v[216:217], v[200:201] op_sel_hi:[0,1]
	v_pk_mul_f32 v[226:227], v[216:217], v[200:201] op_sel:[1,0]
	ds_read_b128 v[28:31], v2 offset:3344
	v_pk_mul_f32 v[220:221], v[216:217], v[202:203] op_sel_hi:[0,1]
	v_pk_mul_f32 v[228:229], v[216:217], v[202:203] op_sel:[1,0]
	ds_read_b128 v[32:35], v2 offset:11520
	v_pk_mul_f32 v[222:223], v[216:217], v[204:205] op_sel_hi:[0,1]
	v_pk_mul_f32 v[230:231], v[216:217], v[204:205] op_sel:[1,0]
	ds_read_b128 v[36:39], v2 offset:11536
	v_pk_mul_f32 v[224:225], v[216:217], v[206:207] op_sel_hi:[0,1]
	v_pk_mul_f32 v[234:235], v[216:217], v[206:207] op_sel:[1,0]
	v_add_f32_e32 v172, v164, v165
	v_add_f32_e32 v174, v166, v167
	v_add_f32_e32 v244, v168, v169
	v_add_f32_e32 v245, v170, v171
	s_waitcnt lgkmcnt(14)
	v_pk_fma_f32 v[218:219], v[72:73], v[184:185], v[218:219]
	v_pk_fma_f32 v[226:227], v[80:81], v[184:185], v[226:227]
	v_pk_fma_f32 v[220:221], v[74:75], v[186:187], v[220:221]
	v_pk_fma_f32 v[228:229], v[82:83], v[186:187], v[228:229]
	v_add_f32_dpp v172, v172, v172 quad_perm:[1,0,3,2] row_mask:0xf bank_mask:0xf bound_ctrl:1
	v_add_f32_dpp v174, v174, v174 quad_perm:[1,0,3,2] row_mask:0xf bank_mask:0xf bound_ctrl:1
	v_add_f32_dpp v244, v244, v244 quad_perm:[1,0,3,2] row_mask:0xf bank_mask:0xf bound_ctrl:1
	v_add_f32_dpp v245, v245, v245 quad_perm:[1,0,3,2] row_mask:0xf bank_mask:0xf bound_ctrl:1
	s_waitcnt lgkmcnt(13)
	v_pk_fma_f32 v[222:223], v[76:77], v[188:189], v[222:223]
	v_pk_fma_f32 v[230:231], v[84:85], v[188:189], v[230:231]
	v_pk_fma_f32 v[224:225], v[78:79], v[190:191], v[224:225]
	v_pk_fma_f32 v[234:235], v[86:87], v[190:191], v[234:235]
	v_add_f32_dpp v172, v172, v172 quad_perm:[2,3,0,1] row_mask:0xf bank_mask:0xf bound_ctrl:1
	v_add_f32_dpp v174, v174, v174 quad_perm:[2,3,0,1] row_mask:0xf bank_mask:0xf bound_ctrl:1
	v_add_f32_dpp v244, v244, v244 quad_perm:[2,3,0,1] row_mask:0xf bank_mask:0xf bound_ctrl:1
	v_add_f32_dpp v245, v245, v245 quad_perm:[2,3,0,1] row_mask:0xf bank_mask:0xf bound_ctrl:1
	v_add_f32_dpp v172, v172, v172 row_half_mirror row_mask:0xf bank_mask:0xf bound_ctrl:1
	v_add_f32_dpp v174, v174, v174 row_half_mirror row_mask:0xf bank_mask:0xf bound_ctrl:1
	v_add_f32_dpp v244, v244, v244 row_half_mirror row_mask:0xf bank_mask:0xf bound_ctrl:1
	v_add_f32_dpp v245, v245, v245 row_half_mirror row_mask:0xf bank_mask:0xf bound_ctrl:1
	s_waitcnt lgkmcnt(12)
	v_pk_fma_f32 v[72:73], v[192:193], v[172:173], v[218:219] op_sel_hi:[1,0,1]
	v_pk_fma_f32 v[80:81], v[192:193], v[174:175], v[226:227] op_sel_hi:[1,0,1]
	v_pk_fma_f32 v[74:75], v[194:195], v[172:173], v[220:221] op_sel_hi:[1,0,1]
	v_pk_fma_f32 v[82:83], v[194:195], v[174:175], v[228:229] op_sel_hi:[1,0,1]
	s_waitcnt lgkmcnt(11)
	v_pk_fma_f32 v[76:77], v[196:197], v[172:173], v[222:223] op_sel_hi:[1,0,1]
	v_pk_fma_f32 v[84:85], v[196:197], v[174:175], v[230:231] op_sel_hi:[1,0,1]
	v_pk_fma_f32 v[78:79], v[198:199], v[172:173], v[224:225] op_sel_hi:[1,0,1]
	v_pk_fma_f32 v[86:87], v[198:199], v[174:175], v[234:235] op_sel_hi:[1,0,1]
	ds_write2_b64 v247, v[160:161], v[244:245] offset0:64 offset1:96
	s_waitcnt lgkmcnt(9)
	v_pk_mul_f32 v[164:165], v[72:73], v[4:5]
	v_pk_mul_f32 v[166:167], v[80:81], v[4:5]
	ds_read_b128 v[48:51], v2 offset:19712
	v_pk_mul_f32 v[168:169], v[72:73], v[208:209]
	v_pk_mul_f32 v[170:171], v[80:81], v[208:209]
	ds_read_b128 v[52:55], v2 offset:19728
	v_pk_fma_f32 v[164:165], v[74:75], v[6:7], v[164:165]
	v_pk_fma_f32 v[166:167], v[82:83], v[6:7], v[166:167]
	ds_read_b128 v[176:179], v2 offset:7680
	v_pk_fma_f32 v[168:169], v[74:75], v[210:211], v[168:169]
	v_pk_fma_f32 v[170:171], v[82:83], v[210:211], v[170:171]
	ds_read_b128 v[180:183], v2 offset:7696
	s_waitcnt lgkmcnt(12)
	v_pk_fma_f32 v[164:165], v[76:77], v[8:9], v[164:165]
	v_pk_fma_f32 v[166:167], v[84:85], v[8:9], v[166:167]
	ds_read_b128 v[200:203], v2 offset:15872
	v_pk_fma_f32 v[168:169], v[76:77], v[212:213], v[168:169]
	v_pk_fma_f32 v[170:171], v[84:85], v[212:213], v[170:171]
	ds_read_b128 v[204:207], v2 offset:15888
	v_pk_fma_f32 v[164:165], v[78:79], v[10:11], v[164:165]
	v_pk_fma_f32 v[166:167], v[86:87], v[10:11], v[166:167]
	ds_read_b64 v[216:217], v3 offset:44544
	v_pk_fma_f32 v[168:169], v[78:79], v[214:215], v[168:169]
	v_pk_fma_f32 v[170:171], v[86:87], v[214:215], v[170:171]
	ds_read_b128 v[184:187], v2 offset:3584
	s_waitcnt lgkmcnt(13)
	v_pk_mul_f32 v[218:219], v[26:27], v[40:41] op_sel_hi:[0,1]
	v_pk_mul_f32 v[226:227], v[26:27], v[40:41] op_sel:[1,0]
	ds_read_b128 v[188:191], v2 offset:3600
	v_pk_mul_f32 v[220:221], v[26:27], v[42:43] op_sel_hi:[0,1]
	v_pk_mul_f32 v[228:229], v[26:27], v[42:43] op_sel:[1,0]
	ds_read_b128 v[192:195], v2 offset:11776
	v_pk_mul_f32 v[222:223], v[26:27], v[44:45] op_sel_hi:[0,1]
	v_pk_mul_f32 v[230:231], v[26:27], v[44:45] op_sel:[1,0]
	ds_read_b128 v[196:199], v2 offset:11792
	v_pk_mul_f32 v[224:225], v[26:27], v[46:47] op_sel_hi:[0,1]
	v_pk_mul_f32 v[234:235], v[26:27], v[46:47] op_sel:[1,0]
	v_add_f32_e32 v172, v164, v165
	v_add_f32_e32 v174, v166, v167
	v_add_f32_e32 v160, v168, v169
	v_add_f32_e32 v161, v170, v171
	s_waitcnt lgkmcnt(15)
	v_pk_fma_f32 v[218:219], v[72:73], v[12:13], v[218:219]
	v_pk_fma_f32 v[226:227], v[80:81], v[12:13], v[226:227]
	v_pk_fma_f32 v[220:221], v[74:75], v[14:15], v[220:221]
	v_pk_fma_f32 v[228:229], v[82:83], v[14:15], v[228:229]
	v_add_f32_dpp v172, v172, v172 quad_perm:[1,0,3,2] row_mask:0xf bank_mask:0xf bound_ctrl:1
	v_add_f32_dpp v174, v174, v174 quad_perm:[1,0,3,2] row_mask:0xf bank_mask:0xf bound_ctrl:1
	v_add_f32_dpp v160, v160, v160 quad_perm:[1,0,3,2] row_mask:0xf bank_mask:0xf bound_ctrl:1
	v_add_f32_dpp v161, v161, v161 quad_perm:[1,0,3,2] row_mask:0xf bank_mask:0xf bound_ctrl:1
	s_waitcnt lgkmcnt(14)
	v_pk_fma_f32 v[222:223], v[76:77], v[28:29], v[222:223]
	v_pk_fma_f32 v[230:231], v[84:85], v[28:29], v[230:231]
	v_pk_fma_f32 v[224:225], v[78:79], v[30:31], v[224:225]
	v_pk_fma_f32 v[234:235], v[86:87], v[30:31], v[234:235]
	v_add_f32_dpp v172, v172, v172 quad_perm:[2,3,0,1] row_mask:0xf bank_mask:0xf bound_ctrl:1
	v_add_f32_dpp v174, v174, v174 quad_perm:[2,3,0,1] row_mask:0xf bank_mask:0xf bound_ctrl:1
	v_add_f32_dpp v160, v160, v160 quad_perm:[2,3,0,1] row_mask:0xf bank_mask:0xf bound_ctrl:1
	v_add_f32_dpp v161, v161, v161 quad_perm:[2,3,0,1] row_mask:0xf bank_mask:0xf bound_ctrl:1
	v_add_f32_dpp v172, v172, v172 row_half_mirror row_mask:0xf bank_mask:0xf bound_ctrl:1
	v_add_f32_dpp v174, v174, v174 row_half_mirror row_mask:0xf bank_mask:0xf bound_ctrl:1
	v_add_f32_dpp v160, v160, v160 row_half_mirror row_mask:0xf bank_mask:0xf bound_ctrl:1
	v_add_f32_dpp v161, v161, v161 row_half_mirror row_mask:0xf bank_mask:0xf bound_ctrl:1
	s_waitcnt lgkmcnt(13)
	v_pk_fma_f32 v[72:73], v[32:33], v[172:173], v[218:219] op_sel_hi:[1,0,1]
	v_pk_fma_f32 v[80:81], v[32:33], v[174:175], v[226:227] op_sel_hi:[1,0,1]
	v_pk_fma_f32 v[74:75], v[34:35], v[172:173], v[220:221] op_sel_hi:[1,0,1]
	v_pk_fma_f32 v[82:83], v[34:35], v[174:175], v[228:229] op_sel_hi:[1,0,1]
	s_waitcnt lgkmcnt(12)
	v_pk_fma_f32 v[76:77], v[36:37], v[172:173], v[222:223] op_sel_hi:[1,0,1]
	v_pk_fma_f32 v[84:85], v[36:37], v[174:175], v[230:231] op_sel_hi:[1,0,1]
	v_pk_fma_f32 v[78:79], v[38:39], v[172:173], v[224:225] op_sel_hi:[1,0,1]
	v_pk_fma_f32 v[86:87], v[38:39], v[174:175], v[234:235] op_sel_hi:[1,0,1]
	s_waitcnt lgkmcnt(8)
	v_pk_mul_f32 v[164:165], v[72:73], v[176:177]
	v_pk_mul_f32 v[166:167], v[80:81], v[176:177]
	ds_read_b128 v[208:211], v2 offset:19968
	v_pk_mul_f32 v[168:169], v[72:73], v[48:49]
	v_pk_mul_f32 v[170:171], v[80:81], v[48:49]
	ds_read_b128 v[212:215], v2 offset:19984
	v_pk_fma_f32 v[164:165], v[74:75], v[178:179], v[164:165]
	v_pk_fma_f32 v[166:167], v[82:83], v[178:179], v[166:167]
	ds_read_b128 v[4:7], v2 offset:7936
	v_pk_fma_f32 v[168:169], v[74:75], v[50:51], v[168:169]
	v_pk_fma_f32 v[170:171], v[82:83], v[50:51], v[170:171]
	ds_read_b128 v[8:11], v2 offset:7952
	s_waitcnt lgkmcnt(11)
	v_pk_fma_f32 v[164:165], v[76:77], v[180:181], v[164:165]
	v_pk_fma_f32 v[166:167], v[84:85], v[180:181], v[166:167]
	ds_read_b128 v[40:43], v2 offset:16128
	v_pk_fma_f32 v[168:169], v[76:77], v[52:53], v[168:169]
	v_pk_fma_f32 v[170:171], v[84:85], v[52:53], v[170:171]
	ds_read_b128 v[44:47], v2 offset:16144
	v_pk_fma_f32 v[164:165], v[78:79], v[182:183], v[164:165]
	v_pk_fma_f32 v[166:167], v[86:87], v[182:183], v[166:167]
	ds_read_b64 v[26:27], v3 offset:44800
	v_pk_fma_f32 v[168:169], v[78:79], v[54:55], v[168:169]
	v_pk_fma_f32 v[170:171], v[86:87], v[54:55], v[170:171]
	ds_read_b128 v[12:15], v2 offset:3840
	s_waitcnt lgkmcnt(12)
	v_pk_mul_f32 v[218:219], v[216:217], v[200:201] op_sel_hi:[0,1]
	v_pk_mul_f32 v[226:227], v[216:217], v[200:201] op_sel:[1,0]
	ds_read_b128 v[28:31], v2 offset:3856
	v_pk_mul_f32 v[220:221], v[216:217], v[202:203] op_sel_hi:[0,1]
	v_pk_mul_f32 v[228:229], v[216:217], v[202:203] op_sel:[1,0]
	ds_read_b128 v[32:35], v2 offset:12032
	v_pk_mul_f32 v[222:223], v[216:217], v[204:205] op_sel_hi:[0,1]
	v_pk_mul_f32 v[230:231], v[216:217], v[204:205] op_sel:[1,0]
	ds_read_b128 v[36:39], v2 offset:12048
	v_pk_mul_f32 v[224:225], v[216:217], v[206:207] op_sel_hi:[0,1]
	v_pk_mul_f32 v[234:235], v[216:217], v[206:207] op_sel:[1,0]
	v_add_f32_e32 v172, v164, v165
	v_add_f32_e32 v174, v166, v167
	v_add_f32_e32 v244, v168, v169
	v_add_f32_e32 v245, v170, v171
	s_waitcnt lgkmcnt(14)
	v_pk_fma_f32 v[218:219], v[72:73], v[184:185], v[218:219]
	v_pk_fma_f32 v[226:227], v[80:81], v[184:185], v[226:227]
	v_pk_fma_f32 v[220:221], v[74:75], v[186:187], v[220:221]
	v_pk_fma_f32 v[228:229], v[82:83], v[186:187], v[228:229]
	v_add_f32_dpp v172, v172, v172 quad_perm:[1,0,3,2] row_mask:0xf bank_mask:0xf bound_ctrl:1
	v_add_f32_dpp v174, v174, v174 quad_perm:[1,0,3,2] row_mask:0xf bank_mask:0xf bound_ctrl:1
	v_add_f32_dpp v244, v244, v244 quad_perm:[1,0,3,2] row_mask:0xf bank_mask:0xf bound_ctrl:1
	v_add_f32_dpp v245, v245, v245 quad_perm:[1,0,3,2] row_mask:0xf bank_mask:0xf bound_ctrl:1
	s_waitcnt lgkmcnt(13)
	v_pk_fma_f32 v[222:223], v[76:77], v[188:189], v[222:223]
	v_pk_fma_f32 v[230:231], v[84:85], v[188:189], v[230:231]
	v_pk_fma_f32 v[224:225], v[78:79], v[190:191], v[224:225]
	v_pk_fma_f32 v[234:235], v[86:87], v[190:191], v[234:235]
	v_add_f32_dpp v172, v172, v172 quad_perm:[2,3,0,1] row_mask:0xf bank_mask:0xf bound_ctrl:1
	v_add_f32_dpp v174, v174, v174 quad_perm:[2,3,0,1] row_mask:0xf bank_mask:0xf bound_ctrl:1
	v_add_f32_dpp v244, v244, v244 quad_perm:[2,3,0,1] row_mask:0xf bank_mask:0xf bound_ctrl:1
	v_add_f32_dpp v245, v245, v245 quad_perm:[2,3,0,1] row_mask:0xf bank_mask:0xf bound_ctrl:1
	v_add_f32_dpp v172, v172, v172 row_half_mirror row_mask:0xf bank_mask:0xf bound_ctrl:1
	v_add_f32_dpp v174, v174, v174 row_half_mirror row_mask:0xf bank_mask:0xf bound_ctrl:1
	v_add_f32_dpp v244, v244, v244 row_half_mirror row_mask:0xf bank_mask:0xf bound_ctrl:1
	v_add_f32_dpp v245, v245, v245 row_half_mirror row_mask:0xf bank_mask:0xf bound_ctrl:1
	s_waitcnt lgkmcnt(12)
	v_pk_fma_f32 v[72:73], v[192:193], v[172:173], v[218:219] op_sel_hi:[1,0,1]
	v_pk_fma_f32 v[80:81], v[192:193], v[174:175], v[226:227] op_sel_hi:[1,0,1]
	v_pk_fma_f32 v[74:75], v[194:195], v[172:173], v[220:221] op_sel_hi:[1,0,1]
	v_pk_fma_f32 v[82:83], v[194:195], v[174:175], v[228:229] op_sel_hi:[1,0,1]
	s_waitcnt lgkmcnt(11)
	v_pk_fma_f32 v[76:77], v[196:197], v[172:173], v[222:223] op_sel_hi:[1,0,1]
	v_pk_fma_f32 v[84:85], v[196:197], v[174:175], v[230:231] op_sel_hi:[1,0,1]
	v_pk_fma_f32 v[78:79], v[198:199], v[172:173], v[224:225] op_sel_hi:[1,0,1]
	v_pk_fma_f32 v[86:87], v[198:199], v[174:175], v[234:235] op_sel_hi:[1,0,1]
	ds_write2_b64 v247, v[160:161], v[244:245] offset0:128 offset1:160
	s_waitcnt lgkmcnt(9)
	v_pk_mul_f32 v[164:165], v[72:73], v[4:5]
	v_pk_mul_f32 v[166:167], v[80:81], v[4:5]
	ds_read_b128 v[48:51], v2 offset:20224
	v_pk_mul_f32 v[168:169], v[72:73], v[208:209]
	v_pk_mul_f32 v[170:171], v[80:81], v[208:209]
	ds_read_b128 v[52:55], v2 offset:20240
	v_pk_fma_f32 v[164:165], v[74:75], v[6:7], v[164:165]
	v_pk_fma_f32 v[166:167], v[82:83], v[6:7], v[166:167]
	v_pk_fma_f32 v[168:169], v[74:75], v[210:211], v[168:169]
	v_pk_fma_f32 v[170:171], v[82:83], v[210:211], v[170:171]
	s_waitcnt lgkmcnt(10)
	v_pk_fma_f32 v[164:165], v[76:77], v[8:9], v[164:165]
	v_pk_fma_f32 v[166:167], v[84:85], v[8:9], v[166:167]
	v_pk_fma_f32 v[168:169], v[76:77], v[212:213], v[168:169]
	v_pk_fma_f32 v[170:171], v[84:85], v[212:213], v[170:171]
	v_pk_fma_f32 v[164:165], v[78:79], v[10:11], v[164:165]
	v_pk_fma_f32 v[166:167], v[86:87], v[10:11], v[166:167]
	v_pk_fma_f32 v[168:169], v[78:79], v[214:215], v[168:169]
	v_pk_fma_f32 v[170:171], v[86:87], v[214:215], v[170:171]
	s_waitcnt lgkmcnt(7)
	v_pk_mul_f32 v[218:219], v[26:27], v[40:41] op_sel_hi:[0,1]
	v_pk_mul_f32 v[226:227], v[26:27], v[40:41] op_sel:[1,0]
	v_pk_mul_f32 v[220:221], v[26:27], v[42:43] op_sel_hi:[0,1]
	v_pk_mul_f32 v[228:229], v[26:27], v[42:43] op_sel:[1,0]
	v_pk_mul_f32 v[222:223], v[26:27], v[44:45] op_sel_hi:[0,1]
	v_pk_mul_f32 v[230:231], v[26:27], v[44:45] op_sel:[1,0]
	v_pk_mul_f32 v[224:225], v[26:27], v[46:47] op_sel_hi:[0,1]
	v_pk_mul_f32 v[234:235], v[26:27], v[46:47] op_sel:[1,0]
	v_add_f32_e32 v172, v164, v165
	v_add_f32_e32 v174, v166, v167
	v_add_f32_e32 v160, v168, v169
	v_add_f32_e32 v161, v170, v171
	s_waitcnt lgkmcnt(6)
	v_pk_fma_f32 v[218:219], v[72:73], v[12:13], v[218:219]
	v_pk_fma_f32 v[226:227], v[80:81], v[12:13], v[226:227]
	v_pk_fma_f32 v[220:221], v[74:75], v[14:15], v[220:221]
	v_pk_fma_f32 v[228:229], v[82:83], v[14:15], v[228:229]
	v_add_f32_dpp v172, v172, v172 quad_perm:[1,0,3,2] row_mask:0xf bank_mask:0xf bound_ctrl:1
	v_add_f32_dpp v174, v174, v174 quad_perm:[1,0,3,2] row_mask:0xf bank_mask:0xf bound_ctrl:1
	v_add_f32_dpp v160, v160, v160 quad_perm:[1,0,3,2] row_mask:0xf bank_mask:0xf bound_ctrl:1
	v_add_f32_dpp v161, v161, v161 quad_perm:[1,0,3,2] row_mask:0xf bank_mask:0xf bound_ctrl:1
	s_waitcnt lgkmcnt(5)
	v_pk_fma_f32 v[222:223], v[76:77], v[28:29], v[222:223]
	v_pk_fma_f32 v[230:231], v[84:85], v[28:29], v[230:231]
	v_pk_fma_f32 v[224:225], v[78:79], v[30:31], v[224:225]
	v_pk_fma_f32 v[234:235], v[86:87], v[30:31], v[234:235]
	v_add_f32_dpp v172, v172, v172 quad_perm:[2,3,0,1] row_mask:0xf bank_mask:0xf bound_ctrl:1
	v_add_f32_dpp v174, v174, v174 quad_perm:[2,3,0,1] row_mask:0xf bank_mask:0xf bound_ctrl:1
	v_add_f32_dpp v160, v160, v160 quad_perm:[2,3,0,1] row_mask:0xf bank_mask:0xf bound_ctrl:1
	v_add_f32_dpp v161, v161, v161 quad_perm:[2,3,0,1] row_mask:0xf bank_mask:0xf bound_ctrl:1
	v_add_f32_dpp v172, v172, v172 row_half_mirror row_mask:0xf bank_mask:0xf bound_ctrl:1
	v_add_f32_dpp v174, v174, v174 row_half_mirror row_mask:0xf bank_mask:0xf bound_ctrl:1
	v_add_f32_dpp v160, v160, v160 row_half_mirror row_mask:0xf bank_mask:0xf bound_ctrl:1
	v_add_f32_dpp v161, v161, v161 row_half_mirror row_mask:0xf bank_mask:0xf bound_ctrl:1
	s_waitcnt lgkmcnt(4)
	v_pk_fma_f32 v[72:73], v[32:33], v[172:173], v[218:219] op_sel_hi:[1,0,1]
	v_pk_fma_f32 v[80:81], v[32:33], v[174:175], v[226:227] op_sel_hi:[1,0,1]
	v_pk_fma_f32 v[74:75], v[34:35], v[172:173], v[220:221] op_sel_hi:[1,0,1]
	v_pk_fma_f32 v[82:83], v[34:35], v[174:175], v[228:229] op_sel_hi:[1,0,1]
	s_waitcnt lgkmcnt(3)
	v_pk_fma_f32 v[76:77], v[36:37], v[172:173], v[222:223] op_sel_hi:[1,0,1]
	v_pk_fma_f32 v[84:85], v[36:37], v[174:175], v[230:231] op_sel_hi:[1,0,1]
	v_pk_fma_f32 v[78:79], v[38:39], v[172:173], v[224:225] op_sel_hi:[1,0,1]
	v_pk_fma_f32 v[86:87], v[38:39], v[174:175], v[234:235] op_sel_hi:[1,0,1]
	s_waitcnt lgkmcnt(1)
	v_pk_mul_f32 v[168:169], v[72:73], v[48:49]
	v_pk_mul_f32 v[170:171], v[80:81], v[48:49]
	v_pk_fma_f32 v[168:169], v[74:75], v[50:51], v[168:169]
	v_pk_fma_f32 v[170:171], v[82:83], v[50:51], v[170:171]
	s_waitcnt lgkmcnt(0)
	v_pk_fma_f32 v[168:169], v[76:77], v[52:53], v[168:169]
	v_pk_fma_f32 v[170:171], v[84:85], v[52:53], v[170:171]
	v_pk_fma_f32 v[168:169], v[78:79], v[54:55], v[168:169]
	v_pk_fma_f32 v[170:171], v[86:87], v[54:55], v[170:171]
	v_add_f32_e32 v244, v168, v169
	v_add_f32_e32 v245, v170, v171
	s_nop 0
	v_add_f32_dpp v244, v244, v244 quad_perm:[1,0,3,2] row_mask:0xf bank_mask:0xf bound_ctrl:1
	v_add_f32_dpp v245, v245, v245 quad_perm:[1,0,3,2] row_mask:0xf bank_mask:0xf bound_ctrl:1
	s_nop 0
	v_add_f32_dpp v244, v244, v244 quad_perm:[2,3,0,1] row_mask:0xf bank_mask:0xf bound_ctrl:1
	v_add_f32_dpp v245, v245, v245 quad_perm:[2,3,0,1] row_mask:0xf bank_mask:0xf bound_ctrl:1
	s_nop 0
	v_add_f32_dpp v244, v244, v244 row_half_mirror row_mask:0xf bank_mask:0xf bound_ctrl:1
	v_add_f32_dpp v245, v245, v245 row_half_mirror row_mask:0xf bank_mask:0xf bound_ctrl:1
	ds_write2_b64 v247, v[160:161], v[244:245] offset0:192 offset1:224
	s_add_i32 s3, s2, 1
	s_mov_b64 s[36:37], 0
